# EpiResid epilogues (P4, P12): the two 8-byte bf16 stores of a row merged into one 16-byte store after a v_permlane16_swap half exchange (T21-style widened store tail); deferred SSQ atomics kept
# speedup vs baseline: 1.0134x; 1.0012x over previous
;     __host__ __device__ bool next(int i, Unit& u) const { const long L = (long)i * G + c; if (L >= nun) return false; u.pz = (int)L / nM; u.pm = (int)L % nM; u.pn = 0; return true; }
;   __device__ __forceinline__ bool next(int i,AttnUnit&u)const{ const int v=vcu+(i>>2)*G; if(v>=256)return false; const int s=v&15,k=i&3; u.bh=v>>4; u.qb=(k&1)?(32*(k>>1)+31-s):(32*(k>>1)+s); return true; }
; #define LAS __attribute__((address_space(3)))
; #define p_x INP(0)
;     __host__ __device__ bool next(int i, Unit& u) const {
;         const long L = (long)i * G + c; if (L >= nwg) return false;
;         int wgid = (int)L; { const int q = nwg / NXCD, r = nwg % NXCD, xcd = wgid % NXCD, off = wgid / NXCD; wgid = (xcd < r ? xcd * (q + 1) : r * (q + 1) + (xcd - r) * q) + off; }
; __device__ __forceinline__ const void* ldptr(LAS unsigned char* L, int k) {
;     const LAS unsigned* t = (const LAS unsigned*)(L + TAB_OFF) + 2 * k;
;     const unsigned lo = __builtin_amdgcn_readfirstlane(t[0]), hi = __builtin_amdgcn_readfirstlane(t[1]);
;     return (const void*)(((unsigned long long)hi << 32) | lo);
; }
; __global__ void __launch_bounds__(NTHR, 2) mk_fwd(Args args) {
;     ...
;     if (IN(4)) { pg8::Gemm g{p_H, p_W1D, FF, FF, FF, 0, 0}; pg8::StaticOrder S; S.init(M, DMODEL, G, bx); pg8::EpiResid<true> Ep{p_x, p_out, DMODEL, p_mod + 2 * DMODEL, p_HB, p_GM, p_SSQ};
;         pg8::gemm_phase<pg8::EpiResid<true>, pg8::StaticOrder, true, true>(L, g, S, Ep, wave); }
.LBB0_473:
	s_cmp_lt_i32 s68, 5
	s_cselect_b64 s[0:1], -1, 0
	s_and_b64 s[6:7], s[0:1], s[34:35]
	s_andn2_b64 vcc, exec, s[6:7]
	s_cbranch_vccnz .LBB0_520
	v_mbcnt_lo_u32_b32 v250, -1, 0
	v_mbcnt_hi_u32_b32 v250, -1, v250
	v_lshrrev_b32_e32 v250, 4, v250
	v_and_b32_e32 v250, 1, v250
	v_mul_u32_u24_e32 v250, 24, v250
	v_mov_b32_e32 v251, 0
	s_add_i32 s0, 0, 0x20110
	v_mov_b32_e32 v0, s0
	s_add_i32 s0, 0, 0x20000
	v_mov_b32_e32 v4, s0
	ds_read_b128 v[0:3], v0
	ds_read_b64 v[4:5], v4
	s_cmpk_lt_i32 s2, 0x200
	s_cselect_b64 s[0:1], -1, 0
	s_cmpk_gt_i32 s2, 0x1ff
	s_waitcnt lgkmcnt(0)
	v_readfirstlane_b32 s20, v2
	v_readfirstlane_b32 s21, v3
	v_readfirstlane_b32 s8, v4
	v_readfirstlane_b32 s9, v5
	v_readfirstlane_b32 s10, v0
	v_readfirstlane_b32 s11, v1
	v_mbcnt_lo_u32_b32 v8, -1, 0
	v_mbcnt_hi_u32_b32 v8, -1, v8
	s_cbranch_scc1 .LBB0_480
	s_ashr_i32 s3, s2, 31
	s_lshr_b32 s3, s3, 29
	s_add_i32 s3, s2, s3
	s_and_b32 s4, s3, -8
	s_sub_i32 s12, s2, s4
	s_cmp_gt_i32 s12, -1
	s_cbranch_scc0 .LBB0_477
	s_lshl_b32 s13, s12, 6
	s_cbranch_execz .LBB0_478
	s_branch .LBB0_479

; __device__ __forceinline__ int lane_asm() { int l; asm volatile("v_mbcnt_lo_u32_b32 %0, -1, 0\n\tv_mbcnt_hi_u32_b32 %0, -1, %0" : "=v"(l)); return l; }
;     __device__ __forceinline__ void operator()(const f32x4 (&acc)[2][2][4][2], const Unit& u, int wr, int wc, int fr_, int fq_) const {
;         const int l_ = lane_asm(); const int fr = l_ & 15, fq = l_ >> 4; (void)fr_; (void)fq_;
;         const int row0 = u.pm * BM + wr * 64 + fr, col0 = u.pn * BM + wc * 32 + 4 * fq;
;         f32x4 gv[2][2], gm[2][2];
; #pragma unroll
;         for (int bj = 0; bj < 2; ++bj)
; #pragma unroll
;             for (int n = 0; n < 2; ++n) { gv[bj][n] = *(const f32x4*)(gate + col0 + bj * HALF + n * 16);
;                 if constexpr (EMIT) gm[bj][n] = *(const f32x4*)(gmv + col0 + bj * HALF + n * 16); else gm[bj][n] = gv[bj][n]; }
; #pragma unroll
;         for (int ai = 0; ai < 2; ++ai)
; #pragma unroll
;         for (int mh = 0; mh < 2; ++mh) {
;             f32x4 bs[2][2][2];
; #pragma unroll
;             for (int m = 0; m < 2; ++m) { const size_t off = (size_t)(row0 + ai * HALF + (2 * mh + m) * 16) * ldc + col0;
; #pragma unroll
;                 for (int bj = 0; bj < 2; ++bj)
; #pragma unroll
;                     for (int n = 0; n < 2; ++n) bs[m][bj][n] = *(const f32x4*)(base + off + bj * HALF + n * 16); }
;             asm volatile("" ::: "memory");
; #pragma unroll
;             for (int m = 0; m < 2; ++m) { const int row = row0 + ai * HALF + (2 * mh + m) * 16; const size_t off = (size_t)row * ldc + col0; float ss = 0.f;
; #pragma unroll
;                 for (int bj = 0; bj < 2; ++bj)
; #pragma unroll
;                     for (int n = 0; n < 2; ++n) { const f32x4 o = bs[m][bj][n] + gv[bj][n] * acc[ai][bj][2 * mh + m][n]; *(f32x4*)(out + off + bj * HALF + n * 16) = o;
;                         if constexpr (EMIT) { ss += (o[0] * o[0] + o[1] * o[1]) + (o[2] * o[2] + o[3] * o[3]); const f32x4 y = o * gm[bj][n];
;                             typedef unsigned u32x2_t __attribute__((ext_vector_type(2))); u32x2_t w; w.x = cvt_pk_bf16(y[0], y[1]); w.y = cvt_pk_bf16(y[2], y[3]); *(u32x2_t*)(A2 + off + bj * HALF + n * 16) = w; } }
;                 if constexpr (EMIT) { ss += __shfl_xor(ss, 16); ss += __shfl_xor(ss, 32); if (fq == 0) atomicAdd(ssq + row, (unsigned long long)(ss * 16777216.0f)); } }
.LBB0_500:
	v_mbcnt_lo_u32_b32 v201, -1, 0
	v_mbcnt_hi_u32_b32 v201, -1, v201
	s_lshl_b32 s5, s57, 8
	v_ashrrev_i32_e32 v64, 2, v201
	s_lshl_b32 s4, s58, 8
	s_or_b32 s5, s5, s47
	v_and_b32_e32 v64, -4, v64
	s_add_i32 s4, s4, s46
	v_add_u32_e32 v188, s5, v64
	v_ashrrev_i32_e32 v189, 31, v188
	v_and_or_b32 v192, v201, 15, s4
	v_lshlrev_b64 v[64:65], 2, v[188:189]
	v_ashrrev_i32_e32 v193, 31, v192
	v_lshl_add_u64 v[190:191], s[8:9], 0, v[64:65]
	v_lshlrev_b64 v[72:73], 13, v[192:193]
	v_lshl_add_u64 v[80:81], v[190:191], 0, v[72:73]
	v_lshl_add_u64 v[66:67], s[14:15], 0, v[64:65]
	global_load_dwordx4 v[202:205], v[80:81], off
	global_load_dwordx4 v[104:107], v[66:67], off
	global_load_dwordx4 v[92:95], v[66:67], off offset:64
	global_load_dwordx4 v[206:209], v[80:81], off offset:64
	global_load_dwordx4 v[210:213], v[80:81], off offset:512
	global_load_dwordx4 v[84:87], v[66:67], off offset:512
	global_load_dwordx4 v[72:75], v[66:67], off offset:576
	global_load_dwordx4 v[214:217], v[80:81], off offset:576
	v_lshl_add_u64 v[64:65], s[18:19], 0, v[64:65]
	global_load_dwordx4 v[100:103], v[64:65], off
	global_load_dwordx4 v[88:91], v[64:65], off offset:64
	global_load_dwordx4 v[80:83], v[64:65], off offset:512
	s_nop 0
	global_load_dwordx4 v[64:67], v[64:65], off offset:576
	v_or_b32_e32 v194, 16, v192
	v_ashrrev_i32_e32 v195, 31, v194
	v_lshlrev_b64 v[160:161], 13, v[194:195]
	v_lshl_add_u64 v[160:161], v[190:191], 0, v[160:161]
	global_load_dwordx4 v[172:175], v[160:161], off
	global_load_dwordx4 v[168:171], v[160:161], off offset:64
	global_load_dwordx4 v[164:167], v[160:161], off offset:512
	s_nop 0
	global_load_dwordx4 v[160:163], v[160:161], off offset:576
	v_and_b32_e32 v219, 64, v200
	v_xor_b32_e32 v218, 16, v200
	v_cmp_gt_u32_e32 vcc, 16, v201
	v_add_u32_e32 v201, 64, v219
	v_cmp_lt_i32_e64 s[4:5], v218, v201
	s_waitcnt vmcnt(0) lgkmcnt(0)
	v_pk_fma_f32 v[158:159], v[158:159], v[106:107], v[204:205]
	v_cndmask_b32_e64 v222, v200, v218, s[4:5]
	v_lshlrev_b64 v[218:219], 11, v[192:193]
	v_lshl_add_u64 v[218:219], v[218:219], 0, v[188:189]
	v_lshl_add_u64 v[220:221], v[218:219], 2, s[10:11]
	v_pk_fma_f32 v[156:157], v[156:157], v[104:105], v[202:203]
	v_pk_fma_f32 v[154:155], v[154:155], v[94:95], v[208:209]
	v_pk_fma_f32 v[152:153], v[152:153], v[92:93], v[206:207]
	v_pk_fma_f32 v[150:151], v[150:151], v[86:87], v[212:213]
	v_pk_fma_f32 v[148:149], v[148:149], v[84:85], v[210:211]
	v_pk_fma_f32 v[204:205], v[146:147], v[74:75], v[216:217]
	v_pk_fma_f32 v[202:203], v[144:145], v[72:73], v[214:215]
	global_store_dwordx4 v[220:221], v[156:159], off
	v_mul_f32_e32 v214, v157, v157
	v_mul_f32_e32 v215, v159, v159
	v_pk_mul_f32 v[144:145], v[102:103], v[158:159]
	v_pk_mul_f32 v[146:147], v[100:101], v[156:157]
	v_mul_f32_e32 v157, v153, v153
	v_mul_f32_e32 v159, v155, v155
	v_lshl_add_u64 v[218:219], v[218:219], 1, s[16:17]
	v_mul_f32_e32 v216, v149, v149
	v_mul_f32_e32 v217, v151, v151
	v_fmac_f32_e32 v214, v156, v156
	v_fmac_f32_e32 v215, v158, v158
	v_cvt_pk_bf16_f32 v244, v146, v147
	v_cvt_pk_bf16_f32 v245, v144, v145
	v_fmac_f32_e32 v157, v152, v152
	v_fmac_f32_e32 v159, v154, v154
	v_mul_f32_e32 v223, v203, v203
	v_mul_f32_e32 v224, v205, v205
	v_fmac_f32_e32 v216, v148, v148
	v_fmac_f32_e32 v217, v150, v150
	v_add_f32_e32 v156, v214, v215
	global_store_dwordx4 v[220:221], v[152:155], off offset:64
	v_add_f32_e32 v146, v157, v159
	v_pk_mul_f32 v[206:207], v[90:91], v[154:155]
	v_pk_mul_f32 v[208:209], v[88:89], v[152:153]
	v_fmac_f32_e32 v223, v202, v202
	v_fmac_f32_e32 v224, v204, v204
	v_cvt_pk_bf16_f32 v246, v208, v209
	v_cvt_pk_bf16_f32 v247, v206, v207
	v_add_f32_e32 v147, v216, v217
	v_add_f32_e32 v146, v156, v146
	v_add_f32_e32 v152, v223, v224
	s_nop 1
	v_permlane16_swap_b32 v244, v246
	v_permlane16_swap_b32 v245, v247
	v_lshl_add_u64 v[248:249], v[218:219], 0, v[250:251]
	global_store_dwordx4 v[248:249], v[244:247], off
	global_store_dwordx4 v[220:221], v[148:151], off offset:512
	v_add_f32_e32 v145, v146, v147
	v_pk_mul_f32 v[212:213], v[80:81], v[148:149]
	v_add_f32_e32 v149, v145, v152
	v_lshlrev_b32_e32 v148, 2, v222
	v_pk_mul_f32 v[210:211], v[82:83], v[150:151]
	ds_bpermute_b32 v150, v148, v149
	v_cvt_pk_bf16_f32 v244, v212, v213
	v_cvt_pk_bf16_f32 v245, v210, v211
	global_store_dwordx4 v[220:221], v[202:205], off offset:576
	v_xor_b32_e32 v145, 32, v200
	v_cmp_lt_i32_e64 s[4:5], v145, v201
	s_waitcnt lgkmcnt(0)
	v_add_f32_e32 v144, v149, v150
	v_pk_mul_f32 v[150:151], v[64:65], v[202:203]
	v_cndmask_b32_e64 v145, v200, v145, s[4:5]
	v_lshlrev_b32_e32 v149, 2, v145
	ds_bpermute_b32 v145, v149, v144
	v_pk_mul_f32 v[146:147], v[66:67], v[204:205]
	v_cvt_pk_bf16_f32 v246, v150, v151
	s_nop 0
	v_cvt_pk_bf16_f32 v247, v146, v147
	s_nop 1
	v_permlane16_swap_b32 v244, v246
	v_permlane16_swap_b32 v245, v247
	v_lshl_add_u64 v[248:249], v[218:219], 0, v[250:251]
	global_store_dwordx4 v[248:249], v[244:247], off offset:256
	s_and_saveexec_b64 s[4:5], vcc
	s_cbranch_execz .LBB0_502
	s_waitcnt lgkmcnt(0)
	v_add_f32_e32 v144, v144, v145
	v_mul_f32_e32 v144, 0x4b800000, v144
	v_trunc_f32_e32 v144, v144
	v_mul_f32_e32 v145, 0x2f800000, v144
	v_floor_f32_e32 v145, v145
	v_fmac_f32_e32 v144, 0xcf800000, v145
	v_cvt_u32_f32_e32 v144, v144
	v_cvt_u32_f32_e32 v145, v145
	v_mov_b32_e32 v226, v144
	v_mov_b32_e32 v227, v145
	v_lshl_add_u64 v[242:243], v[192:193], 3, s[20:21]
; __device__ __forceinline__ unsigned cvt_pk_bf16(float lo, float hi) { unsigned r; asm volatile("v_cvt_pk_bf16_f32 %0, %1, %2" : "=v"(r) : "v"(lo), "v"(hi)); return r; }
;     __device__ __forceinline__ void operator()(const f32x4 (&acc)[2][2][4][2], const Unit& u, int wr, int wc, int fr_, int fq_) const {
;     ...
;         for (int mh = 0; mh < 2; ++mh) {
;             f32x4 bs[2][2][2];
; #pragma unroll
;             for (int m = 0; m < 2; ++m) { const size_t off = (size_t)(row0 + ai * HALF + (2 * mh + m) * 16) * ldc + col0;
; #pragma unroll
;                 for (int bj = 0; bj < 2; ++bj)
; #pragma unroll
;                     for (int n = 0; n < 2; ++n) bs[m][bj][n] = *(const f32x4*)(base + off + bj * HALF + n * 16); }
;             asm volatile("" ::: "memory");
; #pragma unroll
;             for (int m = 0; m < 2; ++m) { const int row = row0 + ai * HALF + (2 * mh + m) * 16; const size_t off = (size_t)row * ldc + col0; float ss = 0.f;
; #pragma unroll
;                 for (int bj = 0; bj < 2; ++bj)
; #pragma unroll
;                     for (int n = 0; n < 2; ++n) { const f32x4 o = bs[m][bj][n] + gv[bj][n] * acc[ai][bj][2 * mh + m][n]; *(f32x4*)(out + off + bj * HALF + n * 16) = o;
;                         if constexpr (EMIT) { ss += (o[0] * o[0] + o[1] * o[1]) + (o[2] * o[2] + o[3] * o[3]); const f32x4 y = o * gm[bj][n];
;                             typedef unsigned u32x2_t __attribute__((ext_vector_type(2))); u32x2_t w; w.x = cvt_pk_bf16(y[0], y[1]); w.y = cvt_pk_bf16(y[2], y[3]); *(u32x2_t*)(A2 + off + bj * HALF + n * 16) = w; } }
;                 if constexpr (EMIT) { ss += __shfl_xor(ss, 16); ss += __shfl_xor(ss, 32); if (fq == 0) atomicAdd(ssq + row, (unsigned long long)(ss * 16777216.0f)); } }
.LBB0_502:
	s_or_b64 exec, exec, s[4:5]
	s_waitcnt lgkmcnt(0)
	v_lshlrev_b64 v[144:145], 11, v[194:195]
	v_lshl_add_u64 v[144:145], v[144:145], 0, v[188:189]
	v_pk_fma_f32 v[142:143], v[142:143], v[106:107], v[174:175]
	v_pk_fma_f32 v[140:141], v[140:141], v[104:105], v[172:173]
	v_lshl_add_u64 v[146:147], v[144:145], 2, s[10:11]
	v_mul_f32_e32 v150, v141, v141
	v_mul_f32_e32 v151, v143, v143
	global_store_dwordx4 v[146:147], v[140:143], off
	v_fmac_f32_e32 v150, v140, v140
	v_fmac_f32_e32 v151, v142, v142
	v_pk_mul_f32 v[142:143], v[102:103], v[142:143]
	v_pk_mul_f32 v[140:141], v[100:101], v[140:141]
	v_pk_fma_f32 v[136:137], v[136:137], v[92:93], v[168:169]
	v_cvt_pk_bf16_f32 v244, v140, v141
	v_cvt_pk_bf16_f32 v245, v142, v143
	v_lshl_add_u64 v[142:143], v[144:145], 1, s[16:17]
	v_pk_fma_f32 v[138:139], v[138:139], v[94:95], v[170:171]
	v_mul_f32_e32 v140, v137, v137
	global_store_dwordx4 v[146:147], v[136:139], off offset:64
	v_fmac_f32_e32 v140, v136, v136
	v_mul_f32_e32 v141, v139, v139
	v_pk_mul_f32 v[136:137], v[88:89], v[136:137]
	v_fmac_f32_e32 v141, v138, v138
	v_pk_mul_f32 v[138:139], v[90:91], v[138:139]
	v_cvt_pk_bf16_f32 v246, v136, v137
	v_pk_fma_f32 v[134:135], v[134:135], v[86:87], v[166:167]
	v_cvt_pk_bf16_f32 v247, v138, v139
	v_pk_fma_f32 v[132:133], v[132:133], v[84:85], v[164:165]
	s_nop 1
	v_permlane16_swap_b32 v244, v246
	v_permlane16_swap_b32 v245, v247
	v_lshl_add_u64 v[248:249], v[142:143], 0, v[250:251]
	global_store_dwordx4 v[248:249], v[244:247], off
	v_mul_f32_e32 v136, v133, v133
	v_mul_f32_e32 v137, v135, v135
	v_add_f32_e32 v150, v150, v151
	v_add_f32_e32 v140, v140, v141
	v_fmac_f32_e32 v136, v132, v132
	v_fmac_f32_e32 v137, v134, v134
	v_add_f32_e32 v140, v150, v140
	global_store_dwordx4 v[146:147], v[132:135], off offset:512
	v_add_f32_e32 v136, v136, v137
	v_add_f32_e32 v137, v140, v136
	v_pk_mul_f32 v[132:133], v[80:81], v[132:133]
	v_pk_mul_f32 v[134:135], v[82:83], v[134:135]
	v_cvt_pk_bf16_f32 v244, v132, v133
	v_pk_fma_f32 v[132:133], v[130:131], v[74:75], v[162:163]
	v_pk_fma_f32 v[130:131], v[128:129], v[72:73], v[160:161]
	v_mul_f32_e32 v129, v133, v133
	v_mul_f32_e32 v128, v131, v131
	v_fmac_f32_e32 v128, v130, v130
	v_fmac_f32_e32 v129, v132, v132
	v_add_f32_e32 v128, v128, v129
	v_add_f32_e32 v128, v137, v128
	ds_bpermute_b32 v129, v148, v128
	v_cvt_pk_bf16_f32 v245, v134, v135
	global_store_dwordx4 v[146:147], v[130:133], off offset:576
	s_waitcnt lgkmcnt(0)
	v_add_f32_e32 v128, v128, v129
	ds_bpermute_b32 v129, v149, v128
	v_pk_mul_f32 v[130:131], v[64:65], v[130:131]
	v_pk_mul_f32 v[132:133], v[66:67], v[132:133]
	v_cvt_pk_bf16_f32 v246, v130, v131
	s_nop 0
	v_cvt_pk_bf16_f32 v247, v132, v133
	s_nop 1
	v_permlane16_swap_b32 v244, v246
	v_permlane16_swap_b32 v245, v247
	v_lshl_add_u64 v[248:249], v[142:143], 0, v[250:251]
	global_store_dwordx4 v[248:249], v[244:247], off offset:256
	s_and_saveexec_b64 s[4:5], vcc
	s_cbranch_execz .LBB0_504
	s_waitcnt lgkmcnt(0)
	v_add_f32_e32 v128, v128, v129
	v_mul_f32_e32 v128, 0x4b800000, v128
	v_trunc_f32_e32 v128, v128
	v_mul_f32_e32 v129, 0x2f800000, v128
	v_floor_f32_e32 v129, v129
	v_fmac_f32_e32 v128, 0xcf800000, v129
	v_cvt_u32_f32_e32 v128, v128
	v_cvt_u32_f32_e32 v129, v129
	v_mov_b32_e32 v228, v128
	v_mov_b32_e32 v229, v129
.LBB0_504:
	s_or_b64 exec, exec, s[4:5]
	v_or_b32_e32 v146, 32, v192
	v_ashrrev_i32_e32 v147, 31, v146
	s_waitcnt lgkmcnt(0)
	v_lshlrev_b64 v[128:129], 13, v[146:147]
	v_lshl_add_u64 v[128:129], v[190:191], 0, v[128:129]
	global_load_dwordx4 v[150:153], v[128:129], off
	global_load_dwordx4 v[154:157], v[128:129], off offset:64
	global_load_dwordx4 v[158:161], v[128:129], off offset:512
	global_load_dwordx4 v[162:165], v[128:129], off offset:576
	v_or_b32_e32 v144, 48, v192
	v_ashrrev_i32_e32 v145, 31, v144
	v_lshlrev_b64 v[128:129], 13, v[144:145]
	v_lshl_add_u64 v[128:129], v[190:191], 0, v[128:129]
	global_load_dwordx4 v[140:143], v[128:129], off
	global_load_dwordx4 v[136:139], v[128:129], off offset:64
	global_load_dwordx4 v[132:135], v[128:129], off offset:512
	s_nop 0
	global_load_dwordx4 v[128:131], v[128:129], off offset:576
	v_lshlrev_b64 v[166:167], 11, v[146:147]
	v_lshl_add_u64 v[166:167], v[166:167], 0, v[188:189]
	v_lshl_add_u64 v[168:169], v[166:167], 2, s[10:11]
	v_lshl_add_u64 v[166:167], v[166:167], 1, s[16:17]
	s_waitcnt vmcnt(0) lgkmcnt(0)
	v_pk_fma_f32 v[126:127], v[126:127], v[106:107], v[152:153]
	v_pk_fma_f32 v[124:125], v[124:125], v[104:105], v[150:151]
	v_pk_fma_f32 v[122:123], v[122:123], v[94:95], v[156:157]
	v_pk_fma_f32 v[120:121], v[120:121], v[92:93], v[154:155]
	v_pk_fma_f32 v[118:119], v[118:119], v[86:87], v[160:161]
	v_pk_fma_f32 v[116:117], v[116:117], v[84:85], v[158:159]
	v_pk_fma_f32 v[152:153], v[114:115], v[74:75], v[164:165]
	v_pk_fma_f32 v[150:151], v[112:113], v[72:73], v[162:163]
	global_store_dwordx4 v[168:169], v[124:127], off
	v_mul_f32_e32 v162, v125, v125
	v_mul_f32_e32 v163, v127, v127
	v_pk_mul_f32 v[112:113], v[102:103], v[126:127]
	v_pk_mul_f32 v[114:115], v[100:101], v[124:125]
	v_mul_f32_e32 v125, v121, v121
	v_mul_f32_e32 v127, v123, v123
	v_mul_f32_e32 v164, v117, v117
	v_mul_f32_e32 v165, v119, v119
	v_fmac_f32_e32 v162, v124, v124
	v_fmac_f32_e32 v163, v126, v126
	v_cvt_pk_bf16_f32 v244, v114, v115
	v_cvt_pk_bf16_f32 v245, v112, v113
	v_fmac_f32_e32 v125, v120, v120
	v_fmac_f32_e32 v127, v122, v122
	v_mul_f32_e32 v170, v151, v151
	v_mul_f32_e32 v171, v153, v153
	v_fmac_f32_e32 v164, v116, v116
	v_fmac_f32_e32 v165, v118, v118
	v_add_f32_e32 v124, v162, v163
	global_store_dwordx4 v[168:169], v[120:123], off offset:64
	v_add_f32_e32 v114, v125, v127
	v_pk_mul_f32 v[154:155], v[90:91], v[122:123]
	v_pk_mul_f32 v[156:157], v[88:89], v[120:121]
	v_fmac_f32_e32 v170, v150, v150
	v_fmac_f32_e32 v171, v152, v152
	v_cvt_pk_bf16_f32 v246, v156, v157
	v_cvt_pk_bf16_f32 v247, v154, v155
	v_add_f32_e32 v115, v164, v165
	v_add_f32_e32 v114, v124, v114
	s_nop 1
	v_permlane16_swap_b32 v244, v246
	v_permlane16_swap_b32 v245, v247
	v_lshl_add_u64 v[248:249], v[166:167], 0, v[250:251]
	global_store_dwordx4 v[248:249], v[244:247], off
	global_store_dwordx4 v[168:169], v[116:119], off offset:512
	v_add_f32_e32 v113, v114, v115
	v_add_f32_e32 v114, v170, v171
	v_pk_mul_f32 v[160:161], v[80:81], v[116:117]
	v_add_f32_e32 v116, v113, v114
	ds_bpermute_b32 v117, v148, v116
	v_pk_mul_f32 v[158:159], v[82:83], v[118:119]
	v_cvt_pk_bf16_f32 v244, v160, v161
	v_pk_mul_f32 v[114:115], v[66:67], v[152:153]
	v_cvt_pk_bf16_f32 v245, v158, v159
	global_store_dwordx4 v[168:169], v[150:153], off offset:576
	s_waitcnt lgkmcnt(0)
	v_add_f32_e32 v112, v116, v117
	ds_bpermute_b32 v113, v149, v112
	v_pk_mul_f32 v[116:117], v[64:65], v[150:151]
	s_nop 0
	v_cvt_pk_bf16_f32 v246, v116, v117
	v_cvt_pk_bf16_f32 v247, v114, v115
	s_nop 1
	v_permlane16_swap_b32 v244, v246
	v_permlane16_swap_b32 v245, v247
	v_lshl_add_u64 v[248:249], v[166:167], 0, v[250:251]
	global_store_dwordx4 v[248:249], v[244:247], off offset:256
	s_and_saveexec_b64 s[4:5], vcc
	s_cbranch_execz .LBB0_506
; __device__ __forceinline__ unsigned cvt_pk_bf16(float lo, float hi) { unsigned r; asm volatile("v_cvt_pk_bf16_f32 %0, %1, %2" : "=v"(r) : "v"(lo), "v"(hi)); return r; }
;     __device__ __forceinline__ void operator()(const f32x4 (&acc)[2][2][4][2], const Unit& u, int wr, int wc, int fr_, int fq_) const {
;     ...
;         for (int mh = 0; mh < 2; ++mh) {
;             f32x4 bs[2][2][2];
; #pragma unroll
;             for (int m = 0; m < 2; ++m) { const size_t off = (size_t)(row0 + ai * HALF + (2 * mh + m) * 16) * ldc + col0;
; #pragma unroll
;                 for (int bj = 0; bj < 2; ++bj)
; #pragma unroll
;                     for (int n = 0; n < 2; ++n) bs[m][bj][n] = *(const f32x4*)(base + off + bj * HALF + n * 16); }
;             asm volatile("" ::: "memory");
; #pragma unroll
;             for (int m = 0; m < 2; ++m) { const int row = row0 + ai * HALF + (2 * mh + m) * 16; const size_t off = (size_t)row * ldc + col0; float ss = 0.f;
; #pragma unroll
;                 for (int bj = 0; bj < 2; ++bj)
; #pragma unroll
;                     for (int n = 0; n < 2; ++n) { const f32x4 o = bs[m][bj][n] + gv[bj][n] * acc[ai][bj][2 * mh + m][n]; *(f32x4*)(out + off + bj * HALF + n * 16) = o;
;                         if constexpr (EMIT) { ss += (o[0] * o[0] + o[1] * o[1]) + (o[2] * o[2] + o[3] * o[3]); const f32x4 y = o * gm[bj][n];
;                             typedef unsigned u32x2_t __attribute__((ext_vector_type(2))); u32x2_t w; w.x = cvt_pk_bf16(y[0], y[1]); w.y = cvt_pk_bf16(y[2], y[3]); *(u32x2_t*)(A2 + off + bj * HALF + n * 16) = w; } }
;                 if constexpr (EMIT) { ss += __shfl_xor(ss, 16); ss += __shfl_xor(ss, 32); if (fq == 0) atomicAdd(ssq + row, (unsigned long long)(ss * 16777216.0f)); } }
	s_waitcnt lgkmcnt(0)
	v_add_f32_e32 v112, v112, v113
	v_mul_f32_e32 v112, 0x4b800000, v112
	v_trunc_f32_e32 v112, v112
	v_mul_f32_e32 v113, 0x2f800000, v112
	v_floor_f32_e32 v113, v113
	v_fmac_f32_e32 v112, 0xcf800000, v113
	v_cvt_u32_f32_e32 v112, v112
	v_cvt_u32_f32_e32 v113, v113
	v_mov_b32_e32 v230, v112
	v_mov_b32_e32 v231, v113
.LBB0_506:
	s_or_b64 exec, exec, s[4:5]
	s_waitcnt lgkmcnt(0)
	v_lshlrev_b64 v[112:113], 11, v[144:145]
	v_lshl_add_u64 v[112:113], v[112:113], 0, v[188:189]
	v_pk_fma_f32 v[110:111], v[110:111], v[106:107], v[142:143]
	v_pk_fma_f32 v[108:109], v[108:109], v[104:105], v[140:141]
	v_lshl_add_u64 v[114:115], v[112:113], 2, s[10:11]
	v_mul_f32_e32 v116, v109, v109
	v_mul_f32_e32 v117, v111, v111
	global_store_dwordx4 v[114:115], v[108:111], off
	v_fmac_f32_e32 v116, v108, v108
	v_fmac_f32_e32 v117, v110, v110
	v_pk_mul_f32 v[110:111], v[102:103], v[110:111]
	v_pk_mul_f32 v[108:109], v[100:101], v[108:109]
	v_pk_fma_f32 v[96:97], v[96:97], v[92:93], v[136:137]
	v_cvt_pk_bf16_f32 v244, v108, v109
	v_cvt_pk_bf16_f32 v245, v110, v111
	v_lshl_add_u64 v[110:111], v[112:113], 1, s[16:17]
	v_pk_fma_f32 v[98:99], v[98:99], v[94:95], v[138:139]
	v_mul_f32_e32 v108, v97, v97
	global_store_dwordx4 v[114:115], v[96:99], off offset:64
	v_fmac_f32_e32 v108, v96, v96
	v_mul_f32_e32 v109, v99, v99
	v_pk_mul_f32 v[96:97], v[88:89], v[96:97]
	v_fmac_f32_e32 v109, v98, v98
	v_pk_mul_f32 v[98:99], v[90:91], v[98:99]
	v_cvt_pk_bf16_f32 v246, v96, v97
	v_pk_fma_f32 v[78:79], v[78:79], v[86:87], v[134:135]
	v_cvt_pk_bf16_f32 v247, v98, v99
	v_pk_fma_f32 v[76:77], v[76:77], v[84:85], v[132:133]
	s_nop 1
	v_permlane16_swap_b32 v244, v246
	v_permlane16_swap_b32 v245, v247
	v_lshl_add_u64 v[248:249], v[110:111], 0, v[250:251]
	global_store_dwordx4 v[248:249], v[244:247], off
	v_mul_f32_e32 v96, v77, v77
	v_mul_f32_e32 v97, v79, v79
	v_add_f32_e32 v116, v116, v117
	v_add_f32_e32 v108, v108, v109
	v_fmac_f32_e32 v96, v76, v76
	v_fmac_f32_e32 v97, v78, v78
	v_add_f32_e32 v108, v116, v108
	global_store_dwordx4 v[114:115], v[76:79], off offset:512
	v_add_f32_e32 v96, v96, v97
	v_add_f32_e32 v99, v108, v96
	v_pk_mul_f32 v[76:77], v[80:81], v[76:77]
	v_pk_mul_f32 v[96:97], v[82:83], v[78:79]
	v_cvt_pk_bf16_f32 v244, v76, v77
	v_pk_fma_f32 v[78:79], v[70:71], v[74:75], v[130:131]
	v_pk_fma_f32 v[76:77], v[68:69], v[72:73], v[128:129]
	v_mul_f32_e32 v69, v79, v79
	v_mul_f32_e32 v68, v77, v77
	v_fmac_f32_e32 v68, v76, v76
	v_fmac_f32_e32 v69, v78, v78
	v_add_f32_e32 v68, v68, v69
	v_add_f32_e32 v68, v99, v68
	ds_bpermute_b32 v69, v148, v68
	v_cvt_pk_bf16_f32 v245, v96, v97
	global_store_dwordx4 v[114:115], v[76:79], off offset:576
	v_pk_mul_f32 v[70:71], v[66:67], v[78:79]
	s_waitcnt lgkmcnt(0)
	v_add_f32_e32 v68, v68, v69
	ds_bpermute_b32 v69, v149, v68
	v_pk_mul_f32 v[76:77], v[64:65], v[76:77]
	s_nop 0
	v_cvt_pk_bf16_f32 v246, v76, v77
	v_cvt_pk_bf16_f32 v247, v70, v71
	s_nop 1
	v_permlane16_swap_b32 v244, v246
	v_permlane16_swap_b32 v245, v247
	v_lshl_add_u64 v[248:249], v[110:111], 0, v[250:251]
	global_store_dwordx4 v[248:249], v[244:247], off offset:256
	s_and_saveexec_b64 s[4:5], vcc
	s_cbranch_execz .LBB0_508
	s_waitcnt lgkmcnt(0)
	v_add_f32_e32 v68, v68, v69
	v_mul_f32_e32 v68, 0x4b800000, v68
	v_trunc_f32_e32 v68, v68
	v_mul_f32_e32 v69, 0x2f800000, v68
	v_floor_f32_e32 v69, v69
	v_fmac_f32_e32 v68, 0xcf800000, v69
	v_cvt_u32_f32_e32 v68, v68
	v_cvt_u32_f32_e32 v69, v69
	v_mov_b32_e32 v232, v68
	v_mov_b32_e32 v233, v69
.LBB0_508:
	s_or_b64 exec, exec, s[4:5]
	v_add_u32_e32 v114, 0x80, v192
	v_ashrrev_i32_e32 v115, 31, v114
	s_waitcnt lgkmcnt(0)
	v_lshlrev_b64 v[68:69], 13, v[114:115]
	v_lshl_add_u64 v[68:69], v[190:191], 0, v[68:69]
	global_load_dwordx4 v[116:119], v[68:69], off
	global_load_dwordx4 v[120:123], v[68:69], off offset:64
	global_load_dwordx4 v[124:127], v[68:69], off offset:512
	global_load_dwordx4 v[128:131], v[68:69], off offset:576
	v_add_u32_e32 v112, 0x90, v192
	v_ashrrev_i32_e32 v113, 31, v112
	v_lshlrev_b64 v[68:69], 13, v[112:113]
	v_lshl_add_u64 v[68:69], v[190:191], 0, v[68:69]
	global_load_dwordx4 v[108:111], v[68:69], off
	global_load_dwordx4 v[96:99], v[68:69], off offset:64
	global_load_dwordx4 v[76:79], v[68:69], off offset:512
	s_nop 0
	global_load_dwordx4 v[68:71], v[68:69], off offset:576
	v_lshlrev_b64 v[132:133], 11, v[114:115]
	v_lshl_add_u64 v[132:133], v[132:133], 0, v[188:189]
	v_lshl_add_u64 v[134:135], v[132:133], 2, s[10:11]
	v_lshl_add_u64 v[132:133], v[132:133], 1, s[16:17]
	s_waitcnt vmcnt(0) lgkmcnt(0)
	v_pk_fma_f32 v[62:63], v[62:63], v[106:107], v[118:119]
	v_pk_fma_f32 v[60:61], v[60:61], v[104:105], v[116:117]
	v_pk_fma_f32 v[58:59], v[58:59], v[94:95], v[122:123]
	v_pk_fma_f32 v[56:57], v[56:57], v[92:93], v[120:121]
	v_pk_fma_f32 v[54:55], v[54:55], v[86:87], v[126:127]
	v_pk_fma_f32 v[52:53], v[52:53], v[84:85], v[124:125]
	v_pk_fma_f32 v[118:119], v[50:51], v[74:75], v[130:131]
	v_pk_fma_f32 v[116:117], v[48:49], v[72:73], v[128:129]
	global_store_dwordx4 v[134:135], v[60:63], off
	v_mul_f32_e32 v128, v61, v61
	v_mul_f32_e32 v129, v63, v63
	v_pk_mul_f32 v[48:49], v[102:103], v[62:63]
	v_pk_mul_f32 v[50:51], v[100:101], v[60:61]
	v_mul_f32_e32 v61, v57, v57
	v_mul_f32_e32 v63, v59, v59
	v_mul_f32_e32 v130, v53, v53
	v_mul_f32_e32 v131, v55, v55
	v_fmac_f32_e32 v128, v60, v60
	v_fmac_f32_e32 v129, v62, v62
	v_cvt_pk_bf16_f32 v244, v50, v51
	v_cvt_pk_bf16_f32 v245, v48, v49
	v_fmac_f32_e32 v61, v56, v56
	v_fmac_f32_e32 v63, v58, v58
	v_mul_f32_e32 v136, v117, v117
	v_mul_f32_e32 v137, v119, v119
	v_fmac_f32_e32 v130, v52, v52
	v_fmac_f32_e32 v131, v54, v54
	v_add_f32_e32 v60, v128, v129
	global_store_dwordx4 v[134:135], v[56:59], off offset:64
	v_add_f32_e32 v50, v61, v63
	v_pk_mul_f32 v[120:121], v[90:91], v[58:59]
	v_pk_mul_f32 v[122:123], v[88:89], v[56:57]
	v_fmac_f32_e32 v136, v116, v116
	v_fmac_f32_e32 v137, v118, v118
	v_cvt_pk_bf16_f32 v246, v122, v123
	v_cvt_pk_bf16_f32 v247, v120, v121
	v_add_f32_e32 v51, v130, v131
	v_add_f32_e32 v50, v60, v50
	s_nop 1
	v_permlane16_swap_b32 v244, v246
	v_permlane16_swap_b32 v245, v247
	v_lshl_add_u64 v[248:249], v[132:133], 0, v[250:251]
	global_store_dwordx4 v[248:249], v[244:247], off
	global_store_dwordx4 v[134:135], v[52:55], off offset:512
	v_add_f32_e32 v49, v50, v51
	v_add_f32_e32 v50, v136, v137
	v_pk_mul_f32 v[126:127], v[80:81], v[52:53]
	v_add_f32_e32 v52, v49, v50
	ds_bpermute_b32 v53, v148, v52
	v_pk_mul_f32 v[124:125], v[82:83], v[54:55]
	v_cvt_pk_bf16_f32 v244, v126, v127
	v_pk_mul_f32 v[50:51], v[66:67], v[118:119]
	v_cvt_pk_bf16_f32 v245, v124, v125
	global_store_dwordx4 v[134:135], v[116:119], off offset:576
	s_waitcnt lgkmcnt(0)
; __device__ __forceinline__ unsigned cvt_pk_bf16(float lo, float hi) { unsigned r; asm volatile("v_cvt_pk_bf16_f32 %0, %1, %2" : "=v"(r) : "v"(lo), "v"(hi)); return r; }
;     __device__ __forceinline__ void operator()(const f32x4 (&acc)[2][2][4][2], const Unit& u, int wr, int wc, int fr_, int fq_) const {
;     ...
;         for (int mh = 0; mh < 2; ++mh) {
;             f32x4 bs[2][2][2];
; #pragma unroll
;             for (int m = 0; m < 2; ++m) { const size_t off = (size_t)(row0 + ai * HALF + (2 * mh + m) * 16) * ldc + col0;
; #pragma unroll
;                 for (int bj = 0; bj < 2; ++bj)
; #pragma unroll
;                     for (int n = 0; n < 2; ++n) bs[m][bj][n] = *(const f32x4*)(base + off + bj * HALF + n * 16); }
;             asm volatile("" ::: "memory");
; #pragma unroll
;             for (int m = 0; m < 2; ++m) { const int row = row0 + ai * HALF + (2 * mh + m) * 16; const size_t off = (size_t)row * ldc + col0; float ss = 0.f;
; #pragma unroll
;                 for (int bj = 0; bj < 2; ++bj)
; #pragma unroll
;                     for (int n = 0; n < 2; ++n) { const f32x4 o = bs[m][bj][n] + gv[bj][n] * acc[ai][bj][2 * mh + m][n]; *(f32x4*)(out + off + bj * HALF + n * 16) = o;
;                         if constexpr (EMIT) { ss += (o[0] * o[0] + o[1] * o[1]) + (o[2] * o[2] + o[3] * o[3]); const f32x4 y = o * gm[bj][n];
;                             typedef unsigned u32x2_t __attribute__((ext_vector_type(2))); u32x2_t w; w.x = cvt_pk_bf16(y[0], y[1]); w.y = cvt_pk_bf16(y[2], y[3]); *(u32x2_t*)(A2 + off + bj * HALF + n * 16) = w; } }
;                 if constexpr (EMIT) { ss += __shfl_xor(ss, 16); ss += __shfl_xor(ss, 32); if (fq == 0) atomicAdd(ssq + row, (unsigned long long)(ss * 16777216.0f)); } }
	v_add_f32_e32 v48, v52, v53
	ds_bpermute_b32 v49, v149, v48
	v_pk_mul_f32 v[52:53], v[64:65], v[116:117]
	s_nop 0
	v_cvt_pk_bf16_f32 v246, v52, v53
	v_cvt_pk_bf16_f32 v247, v50, v51
	s_nop 1
	v_permlane16_swap_b32 v244, v246
	v_permlane16_swap_b32 v245, v247
	v_lshl_add_u64 v[248:249], v[132:133], 0, v[250:251]
	global_store_dwordx4 v[248:249], v[244:247], off offset:256
	s_and_saveexec_b64 s[4:5], vcc
	s_cbranch_execz .LBB0_510
	s_waitcnt lgkmcnt(0)
	v_add_f32_e32 v48, v48, v49
	v_mul_f32_e32 v48, 0x4b800000, v48
	v_trunc_f32_e32 v48, v48
	v_mul_f32_e32 v49, 0x2f800000, v48
	v_floor_f32_e32 v49, v49
	v_fmac_f32_e32 v48, 0xcf800000, v49
	v_cvt_u32_f32_e32 v48, v48
	v_cvt_u32_f32_e32 v49, v49
	v_mov_b32_e32 v234, v48
	v_mov_b32_e32 v235, v49
.LBB0_510:
	s_or_b64 exec, exec, s[4:5]
	s_waitcnt lgkmcnt(0)
	v_lshlrev_b64 v[48:49], 11, v[112:113]
	v_lshl_add_u64 v[48:49], v[48:49], 0, v[188:189]
	v_pk_fma_f32 v[46:47], v[46:47], v[106:107], v[110:111]
	v_pk_fma_f32 v[44:45], v[44:45], v[104:105], v[108:109]
	v_lshl_add_u64 v[50:51], v[48:49], 2, s[10:11]
	v_mul_f32_e32 v52, v45, v45
	v_mul_f32_e32 v53, v47, v47
	global_store_dwordx4 v[50:51], v[44:47], off
	v_fmac_f32_e32 v52, v44, v44
	v_fmac_f32_e32 v53, v46, v46
	v_pk_mul_f32 v[46:47], v[102:103], v[46:47]
	v_pk_mul_f32 v[44:45], v[100:101], v[44:45]
	v_pk_fma_f32 v[40:41], v[40:41], v[92:93], v[96:97]
	v_cvt_pk_bf16_f32 v244, v44, v45
	v_cvt_pk_bf16_f32 v245, v46, v47
	v_lshl_add_u64 v[46:47], v[48:49], 1, s[16:17]
	v_pk_fma_f32 v[42:43], v[42:43], v[94:95], v[98:99]
	v_mul_f32_e32 v44, v41, v41
	global_store_dwordx4 v[50:51], v[40:43], off offset:64
	v_fmac_f32_e32 v44, v40, v40
	v_mul_f32_e32 v45, v43, v43
	v_pk_mul_f32 v[40:41], v[88:89], v[40:41]
	v_fmac_f32_e32 v45, v42, v42
	v_pk_mul_f32 v[42:43], v[90:91], v[42:43]
	v_cvt_pk_bf16_f32 v246, v40, v41
	v_pk_fma_f32 v[38:39], v[38:39], v[86:87], v[78:79]
	v_cvt_pk_bf16_f32 v247, v42, v43
	v_pk_fma_f32 v[36:37], v[36:37], v[84:85], v[76:77]
	s_nop 1
	v_permlane16_swap_b32 v244, v246
	v_permlane16_swap_b32 v245, v247
	v_lshl_add_u64 v[248:249], v[46:47], 0, v[250:251]
	global_store_dwordx4 v[248:249], v[244:247], off
	v_mul_f32_e32 v40, v37, v37
	v_mul_f32_e32 v41, v39, v39
	v_add_f32_e32 v52, v52, v53
	v_add_f32_e32 v44, v44, v45
	v_fmac_f32_e32 v40, v36, v36
	v_fmac_f32_e32 v41, v38, v38
	v_add_f32_e32 v44, v52, v44
	global_store_dwordx4 v[50:51], v[36:39], off offset:512
	v_add_f32_e32 v40, v40, v41
	v_add_f32_e32 v41, v44, v40
	v_pk_mul_f32 v[36:37], v[80:81], v[36:37]
	v_pk_mul_f32 v[38:39], v[82:83], v[38:39]
	v_cvt_pk_bf16_f32 v244, v36, v37
	v_pk_fma_f32 v[36:37], v[34:35], v[74:75], v[70:71]
	v_pk_fma_f32 v[34:35], v[32:33], v[72:73], v[68:69]
	v_mul_f32_e32 v33, v37, v37
	v_mul_f32_e32 v32, v35, v35
	v_fmac_f32_e32 v32, v34, v34
	v_fmac_f32_e32 v33, v36, v36
	v_add_f32_e32 v32, v32, v33
	v_add_f32_e32 v32, v41, v32
	ds_bpermute_b32 v33, v148, v32
	v_cvt_pk_bf16_f32 v245, v38, v39
	global_store_dwordx4 v[50:51], v[34:37], off offset:576
	s_waitcnt lgkmcnt(0)
	v_add_f32_e32 v32, v32, v33
	ds_bpermute_b32 v33, v149, v32
	v_pk_mul_f32 v[34:35], v[64:65], v[34:35]
	v_pk_mul_f32 v[36:37], v[66:67], v[36:37]
	v_cvt_pk_bf16_f32 v246, v34, v35
	s_nop 0
	v_cvt_pk_bf16_f32 v247, v36, v37
	s_nop 1
	v_permlane16_swap_b32 v244, v246
	v_permlane16_swap_b32 v245, v247
	v_lshl_add_u64 v[248:249], v[46:47], 0, v[250:251]
	global_store_dwordx4 v[248:249], v[244:247], off offset:256
	s_and_saveexec_b64 s[4:5], vcc
	s_cbranch_execz .LBB0_512
	s_waitcnt lgkmcnt(0)
	v_add_f32_e32 v32, v32, v33
	v_mul_f32_e32 v32, 0x4b800000, v32
	v_trunc_f32_e32 v32, v32
	v_mul_f32_e32 v33, 0x2f800000, v32
	v_floor_f32_e32 v33, v33
	v_fmac_f32_e32 v32, 0xcf800000, v33
	v_cvt_u32_f32_e32 v32, v32
	v_cvt_u32_f32_e32 v33, v33
	v_mov_b32_e32 v236, v32
	v_mov_b32_e32 v237, v33
.LBB0_512:
	s_or_b64 exec, exec, s[4:5]
	v_add_u32_e32 v50, 0xa0, v192
	v_ashrrev_i32_e32 v51, 31, v50
	s_waitcnt lgkmcnt(0)
	v_lshlrev_b64 v[32:33], 13, v[50:51]
	v_lshl_add_u64 v[32:33], v[190:191], 0, v[32:33]
	global_load_dwordx4 v[52:55], v[32:33], off
	global_load_dwordx4 v[56:59], v[32:33], off offset:64
	global_load_dwordx4 v[60:63], v[32:33], off offset:512
	global_load_dwordx4 v[68:71], v[32:33], off offset:576
	v_add_u32_e32 v48, 0xb0, v192
	v_ashrrev_i32_e32 v49, 31, v48
	v_lshlrev_b64 v[32:33], 13, v[48:49]
	v_lshl_add_u64 v[32:33], v[190:191], 0, v[32:33]
	global_load_dwordx4 v[44:47], v[32:33], off
	global_load_dwordx4 v[40:43], v[32:33], off offset:64
	global_load_dwordx4 v[36:39], v[32:33], off offset:512
	s_nop 0
	global_load_dwordx4 v[32:35], v[32:33], off offset:576
	v_lshlrev_b64 v[76:77], 11, v[50:51]
	v_lshl_add_u64 v[76:77], v[76:77], 0, v[188:189]
	v_lshl_add_u64 v[78:79], v[76:77], 2, s[10:11]
	v_lshl_add_u64 v[76:77], v[76:77], 1, s[16:17]
	s_waitcnt vmcnt(0) lgkmcnt(0)
; __device__ __forceinline__ unsigned cvt_pk_bf16(float lo, float hi) { unsigned r; asm volatile("v_cvt_pk_bf16_f32 %0, %1, %2" : "=v"(r) : "v"(lo), "v"(hi)); return r; }
;     __device__ __forceinline__ void operator()(const f32x4 (&acc)[2][2][4][2], const Unit& u, int wr, int wc, int fr_, int fq_) const {
;     ...
;         for (int mh = 0; mh < 2; ++mh) {
;             f32x4 bs[2][2][2];
; #pragma unroll
;             for (int m = 0; m < 2; ++m) { const size_t off = (size_t)(row0 + ai * HALF + (2 * mh + m) * 16) * ldc + col0;
; #pragma unroll
;                 for (int bj = 0; bj < 2; ++bj)
; #pragma unroll
;                     for (int n = 0; n < 2; ++n) bs[m][bj][n] = *(const f32x4*)(base + off + bj * HALF + n * 16); }
;             asm volatile("" ::: "memory");
; #pragma unroll
;             for (int m = 0; m < 2; ++m) { const int row = row0 + ai * HALF + (2 * mh + m) * 16; const size_t off = (size_t)row * ldc + col0; float ss = 0.f;
; #pragma unroll
;                 for (int bj = 0; bj < 2; ++bj)
; #pragma unroll
;                     for (int n = 0; n < 2; ++n) { const f32x4 o = bs[m][bj][n] + gv[bj][n] * acc[ai][bj][2 * mh + m][n]; *(f32x4*)(out + off + bj * HALF + n * 16) = o;
;                         if constexpr (EMIT) { ss += (o[0] * o[0] + o[1] * o[1]) + (o[2] * o[2] + o[3] * o[3]); const f32x4 y = o * gm[bj][n];
;                             typedef unsigned u32x2_t __attribute__((ext_vector_type(2))); u32x2_t w; w.x = cvt_pk_bf16(y[0], y[1]); w.y = cvt_pk_bf16(y[2], y[3]); *(u32x2_t*)(A2 + off + bj * HALF + n * 16) = w; } }
;                 if constexpr (EMIT) { ss += __shfl_xor(ss, 16); ss += __shfl_xor(ss, 32); if (fq == 0) atomicAdd(ssq + row, (unsigned long long)(ss * 16777216.0f)); } }
	v_pk_fma_f32 v[30:31], v[30:31], v[106:107], v[54:55]
	v_pk_fma_f32 v[28:29], v[28:29], v[104:105], v[52:53]
	v_pk_fma_f32 v[26:27], v[26:27], v[94:95], v[58:59]
	v_pk_fma_f32 v[24:25], v[24:25], v[92:93], v[56:57]
	v_pk_fma_f32 v[22:23], v[22:23], v[86:87], v[62:63]
	v_pk_fma_f32 v[20:21], v[20:21], v[84:85], v[60:61]
	v_pk_fma_f32 v[54:55], v[18:19], v[74:75], v[70:71]
	v_pk_fma_f32 v[52:53], v[16:17], v[72:73], v[68:69]
	global_store_dwordx4 v[78:79], v[28:31], off
	v_mul_f32_e32 v68, v29, v29
	v_mul_f32_e32 v69, v31, v31
	v_pk_mul_f32 v[16:17], v[102:103], v[30:31]
	v_pk_mul_f32 v[18:19], v[100:101], v[28:29]
	v_mul_f32_e32 v29, v25, v25
	v_mul_f32_e32 v31, v27, v27
	v_mul_f32_e32 v70, v21, v21
	v_mul_f32_e32 v71, v23, v23
	v_fmac_f32_e32 v68, v28, v28
	v_fmac_f32_e32 v69, v30, v30
	v_cvt_pk_bf16_f32 v244, v18, v19
	v_cvt_pk_bf16_f32 v245, v16, v17
	v_fmac_f32_e32 v29, v24, v24
	v_fmac_f32_e32 v31, v26, v26
	v_mul_f32_e32 v96, v53, v53
	v_mul_f32_e32 v97, v55, v55
	v_fmac_f32_e32 v70, v20, v20
	v_fmac_f32_e32 v71, v22, v22
	v_add_f32_e32 v28, v68, v69
	global_store_dwordx4 v[78:79], v[24:27], off offset:64
	v_add_f32_e32 v18, v29, v31
	v_pk_mul_f32 v[56:57], v[90:91], v[26:27]
	v_pk_mul_f32 v[58:59], v[88:89], v[24:25]
	v_fmac_f32_e32 v96, v52, v52
	v_fmac_f32_e32 v97, v54, v54
	v_cvt_pk_bf16_f32 v246, v58, v59
	v_cvt_pk_bf16_f32 v247, v56, v57
	v_add_f32_e32 v19, v70, v71
	v_add_f32_e32 v18, v28, v18
	s_nop 1
	v_permlane16_swap_b32 v244, v246
	v_permlane16_swap_b32 v245, v247
	v_lshl_add_u64 v[248:249], v[76:77], 0, v[250:251]
	global_store_dwordx4 v[248:249], v[244:247], off
	global_store_dwordx4 v[78:79], v[20:23], off offset:512
	v_add_f32_e32 v17, v18, v19
	v_add_f32_e32 v18, v96, v97
	v_pk_mul_f32 v[62:63], v[80:81], v[20:21]
	v_add_f32_e32 v20, v17, v18
	ds_bpermute_b32 v21, v148, v20
	v_pk_mul_f32 v[60:61], v[82:83], v[22:23]
	v_cvt_pk_bf16_f32 v244, v62, v63
	v_pk_mul_f32 v[18:19], v[66:67], v[54:55]
	v_cvt_pk_bf16_f32 v245, v60, v61
	global_store_dwordx4 v[78:79], v[52:55], off offset:576
	s_waitcnt lgkmcnt(0)
	v_add_f32_e32 v16, v20, v21
	ds_bpermute_b32 v17, v149, v16
	v_pk_mul_f32 v[20:21], v[64:65], v[52:53]
	s_nop 0
	v_cvt_pk_bf16_f32 v246, v20, v21
	v_cvt_pk_bf16_f32 v247, v18, v19
	s_nop 1
	v_permlane16_swap_b32 v244, v246
	v_permlane16_swap_b32 v245, v247
	v_lshl_add_u64 v[248:249], v[76:77], 0, v[250:251]
	global_store_dwordx4 v[248:249], v[244:247], off offset:256
	s_and_saveexec_b64 s[4:5], vcc
	s_cbranch_execz .LBB0_514
	s_waitcnt lgkmcnt(0)
	v_add_f32_e32 v16, v16, v17
	v_mul_f32_e32 v16, 0x4b800000, v16
	v_trunc_f32_e32 v16, v16
	v_mul_f32_e32 v17, 0x2f800000, v16
	v_floor_f32_e32 v17, v17
	v_fmac_f32_e32 v16, 0xcf800000, v17
	v_cvt_u32_f32_e32 v16, v16
	v_cvt_u32_f32_e32 v17, v17
	v_mov_b32_e32 v238, v16
	v_mov_b32_e32 v239, v17
.LBB0_514:
	s_or_b64 exec, exec, s[4:5]
	s_waitcnt lgkmcnt(0)
	v_lshlrev_b64 v[16:17], 11, v[48:49]
	v_lshl_add_u64 v[16:17], v[16:17], 0, v[188:189]
	v_pk_fma_f32 v[14:15], v[14:15], v[106:107], v[46:47]
	v_pk_fma_f32 v[12:13], v[12:13], v[104:105], v[44:45]
	v_lshl_add_u64 v[18:19], v[16:17], 2, s[10:11]
	v_mul_f32_e32 v20, v13, v13
	v_mul_f32_e32 v21, v15, v15
	global_store_dwordx4 v[18:19], v[12:15], off
	v_fmac_f32_e32 v20, v12, v12
	v_fmac_f32_e32 v21, v14, v14
	v_pk_mul_f32 v[14:15], v[102:103], v[14:15]
	v_pk_mul_f32 v[12:13], v[100:101], v[12:13]
	v_pk_fma_f32 v[8:9], v[8:9], v[92:93], v[40:41]
	v_cvt_pk_bf16_f32 v244, v12, v13
	v_cvt_pk_bf16_f32 v245, v14, v15
	v_lshl_add_u64 v[14:15], v[16:17], 1, s[16:17]
	v_pk_fma_f32 v[10:11], v[10:11], v[94:95], v[42:43]
	v_mul_f32_e32 v12, v9, v9
	global_store_dwordx4 v[18:19], v[8:11], off offset:64
	v_fmac_f32_e32 v12, v8, v8
	v_mul_f32_e32 v13, v11, v11
	v_pk_mul_f32 v[8:9], v[88:89], v[8:9]
	v_fmac_f32_e32 v13, v10, v10
	v_pk_mul_f32 v[10:11], v[90:91], v[10:11]
	v_cvt_pk_bf16_f32 v246, v8, v9
	v_pk_fma_f32 v[6:7], v[6:7], v[86:87], v[38:39]
	v_cvt_pk_bf16_f32 v247, v10, v11
	v_pk_fma_f32 v[4:5], v[4:5], v[84:85], v[36:37]
	s_nop 1
	v_permlane16_swap_b32 v244, v246
	v_permlane16_swap_b32 v245, v247
	v_lshl_add_u64 v[248:249], v[14:15], 0, v[250:251]
	global_store_dwordx4 v[248:249], v[244:247], off
	v_mul_f32_e32 v8, v5, v5
	v_mul_f32_e32 v9, v7, v7
	v_add_f32_e32 v20, v20, v21
	v_add_f32_e32 v12, v12, v13
	v_fmac_f32_e32 v8, v4, v4
	v_fmac_f32_e32 v9, v6, v6
	v_add_f32_e32 v12, v20, v12
	global_store_dwordx4 v[18:19], v[4:7], off offset:512
	v_add_f32_e32 v8, v8, v9
	v_add_f32_e32 v9, v12, v8
	v_pk_mul_f32 v[4:5], v[80:81], v[4:5]
	v_pk_mul_f32 v[6:7], v[82:83], v[6:7]
	v_cvt_pk_bf16_f32 v244, v4, v5
	v_pk_fma_f32 v[4:5], v[2:3], v[74:75], v[34:35]
	v_pk_fma_f32 v[2:3], v[0:1], v[72:73], v[32:33]
	v_mul_f32_e32 v1, v5, v5
	v_mul_f32_e32 v0, v3, v3
	v_fmac_f32_e32 v0, v2, v2
	v_fmac_f32_e32 v1, v4, v4
	v_add_f32_e32 v0, v0, v1
	v_add_f32_e32 v0, v9, v0
	ds_bpermute_b32 v1, v148, v0
	v_cvt_pk_bf16_f32 v245, v6, v7
	global_store_dwordx4 v[18:19], v[2:5], off offset:576
	s_waitcnt lgkmcnt(0)
	v_add_f32_e32 v0, v0, v1
	ds_bpermute_b32 v1, v149, v0
	v_pk_mul_f32 v[2:3], v[64:65], v[2:3]
	v_pk_mul_f32 v[4:5], v[66:67], v[4:5]
	v_cvt_pk_bf16_f32 v246, v2, v3
	s_nop 0
	v_cvt_pk_bf16_f32 v247, v4, v5
	s_nop 1
	v_permlane16_swap_b32 v244, v246
	v_permlane16_swap_b32 v245, v247
	v_lshl_add_u64 v[248:249], v[14:15], 0, v[250:251]
	global_store_dwordx4 v[248:249], v[244:247], off offset:256
	s_and_saveexec_b64 s[4:5], vcc
	s_cbranch_execz .LBB0_516
	s_waitcnt lgkmcnt(0)
	v_add_f32_e32 v0, v0, v1
	v_mul_f32_e32 v0, 0x4b800000, v0
	v_trunc_f32_e32 v0, v0
	v_mul_f32_e32 v1, 0x2f800000, v0
	v_floor_f32_e32 v1, v1
	v_fmac_f32_e32 v0, 0xcf800000, v1
	v_cvt_u32_f32_e32 v0, v0
	v_cvt_u32_f32_e32 v1, v1
	v_mov_b32_e32 v240, v0
	v_mov_b32_e32 v241, v1
	global_atomic_add_x2 v[242:243], v[226:227], off
	global_atomic_add_x2 v[242:243], v[228:229], off offset:128
	global_atomic_add_x2 v[242:243], v[230:231], off offset:256
	global_atomic_add_x2 v[242:243], v[232:233], off offset:384
	global_atomic_add_x2 v[242:243], v[234:235], off offset:1024
	global_atomic_add_x2 v[242:243], v[236:237], off offset:1152
	global_atomic_add_x2 v[242:243], v[238:239], off offset:1280
	global_atomic_add_x2 v[242:243], v[240:241], off offset:1408

; __device__ __forceinline__ int lane_asm() { int l; asm volatile("v_mbcnt_lo_u32_b32 %0, -1, 0\n\tv_mbcnt_hi_u32_b32 %0, -1, %0" : "=v"(l)); return l; }
;     __device__ __forceinline__ void operator()(const f32x4 (&acc)[2][2][4][2], const Unit& u, int wr, int wc, int fr_, int fq_) const {
;         const int l_ = lane_asm(); const int fr = l_ & 15, fq = l_ >> 4; (void)fr_; (void)fq_;
;         const int row0 = u.pm * BM + wr * 64 + fr, col0 = u.pn * BM + wc * 32 + 4 * fq;
;         f32x4 gv[2][2], gm[2][2];
; #pragma unroll
;         for (int bj = 0; bj < 2; ++bj)
; #pragma unroll
;             for (int n = 0; n < 2; ++n) { gv[bj][n] = *(const f32x4*)(gate + col0 + bj * HALF + n * 16);
;                 if constexpr (EMIT) gm[bj][n] = *(const f32x4*)(gmv + col0 + bj * HALF + n * 16); else gm[bj][n] = gv[bj][n]; }
; #pragma unroll
;         for (int ai = 0; ai < 2; ++ai)
; #pragma unroll
;         for (int mh = 0; mh < 2; ++mh) {
;             f32x4 bs[2][2][2];
; #pragma unroll
;             for (int m = 0; m < 2; ++m) { const size_t off = (size_t)(row0 + ai * HALF + (2 * mh + m) * 16) * ldc + col0;
; #pragma unroll
;                 for (int bj = 0; bj < 2; ++bj)
; #pragma unroll
;                     for (int n = 0; n < 2; ++n) bs[m][bj][n] = *(const f32x4*)(base + off + bj * HALF + n * 16); }
;             asm volatile("" ::: "memory");
; #pragma unroll
;             for (int m = 0; m < 2; ++m) { const int row = row0 + ai * HALF + (2 * mh + m) * 16; const size_t off = (size_t)row * ldc + col0; float ss = 0.f;
; #pragma unroll
;                 for (int bj = 0; bj < 2; ++bj)
; #pragma unroll
;                     for (int n = 0; n < 2; ++n) { const f32x4 o = bs[m][bj][n] + gv[bj][n] * acc[ai][bj][2 * mh + m][n]; *(f32x4*)(out + off + bj * HALF + n * 16) = o;
;                         if constexpr (EMIT) { ss += (o[0] * o[0] + o[1] * o[1]) + (o[2] * o[2] + o[3] * o[3]); const f32x4 y = o * gm[bj][n];
;                             typedef unsigned u32x2_t __attribute__((ext_vector_type(2))); u32x2_t w; w.x = cvt_pk_bf16(y[0], y[1]); w.y = cvt_pk_bf16(y[2], y[3]); *(u32x2_t*)(A2 + off + bj * HALF + n * 16) = w; } }
;                 if constexpr (EMIT) { ss += __shfl_xor(ss, 16); ss += __shfl_xor(ss, 32); if (fq == 0) atomicAdd(ssq + row, (unsigned long long)(ss * 16777216.0f)); } }
.LBB0_1307:
	v_mbcnt_lo_u32_b32 v203, -1, 0
	v_mbcnt_hi_u32_b32 v203, -1, v203
	s_lshl_b32 s4, s4, 8
	v_ashrrev_i32_e32 v64, 2, v203
	s_lshl_b32 s5, s34, 8
	s_or_b32 s4, s4, s50
	v_and_b32_e32 v64, -4, v64
	s_add_i32 s5, s5, s49
	v_add_u32_e32 v188, s4, v64
	v_ashrrev_i32_e32 v189, 31, v188
	v_and_or_b32 v192, v203, 15, s5
	v_lshlrev_b64 v[64:65], 2, v[188:189]
	v_ashrrev_i32_e32 v193, 31, v192
	v_lshl_add_u64 v[190:191], s[8:9], 0, v[64:65]
	v_lshlrev_b64 v[72:73], 13, v[192:193]
	v_lshl_add_u64 v[220:221], v[190:191], 0, v[72:73]
	v_lshl_add_u64 v[66:67], s[12:13], 0, v[64:65]
	global_load_dwordx4 v[204:207], v[220:221], off
	global_load_dwordx4 v[104:107], v[66:67], off
	global_load_dwordx4 v[92:95], v[66:67], off offset:64
	global_load_dwordx4 v[208:211], v[220:221], off offset:64
	global_load_dwordx4 v[212:215], v[220:221], off offset:512
	global_load_dwordx4 v[84:87], v[66:67], off offset:512
	global_load_dwordx4 v[72:75], v[66:67], off offset:576
	global_load_dwordx4 v[216:219], v[220:221], off offset:576
	v_lshl_add_u64 v[64:65], s[16:17], 0, v[64:65]
	global_load_dwordx4 v[100:103], v[64:65], off
	global_load_dwordx4 v[88:91], v[64:65], off offset:64
	global_load_dwordx4 v[80:83], v[64:65], off offset:512
	s_nop 0
	global_load_dwordx4 v[64:67], v[64:65], off offset:576
	v_or_b32_e32 v194, 16, v192
	v_ashrrev_i32_e32 v195, 31, v194
	v_lshlrev_b64 v[160:161], 13, v[194:195]
	v_lshl_add_u64 v[196:197], v[190:191], 0, v[160:161]
	global_load_dwordx4 v[172:175], v[196:197], off
	global_load_dwordx4 v[168:171], v[196:197], off offset:64
	global_load_dwordx4 v[164:167], v[196:197], off offset:512
	global_load_dwordx4 v[160:163], v[196:197], off offset:576
	v_and_b32_e32 v223, 64, v202
	v_xor_b32_e32 v222, 16, v202
	v_add_u32_e32 v224, 64, v223
	v_cmp_lt_i32_e64 s[4:5], v222, v224
	v_cmp_gt_u32_e32 vcc, 16, v203
	s_waitcnt vmcnt(0) lgkmcnt(0)
	v_pk_fma_f32 v[158:159], v[158:159], v[106:107], v[206:207]
	v_cndmask_b32_e64 v203, v202, v222, s[4:5]
	v_lshlrev_b64 v[222:223], 11, v[192:193]
	v_pk_fma_f32 v[156:157], v[156:157], v[104:105], v[204:205]
	v_pk_fma_f32 v[154:155], v[154:155], v[94:95], v[210:211]
	v_pk_fma_f32 v[152:153], v[152:153], v[92:93], v[208:209]
	v_lshl_add_u64 v[222:223], v[222:223], 0, v[188:189]
	v_pk_fma_f32 v[150:151], v[150:151], v[86:87], v[214:215]
	v_pk_fma_f32 v[148:149], v[148:149], v[84:85], v[212:213]
	v_pk_fma_f32 v[206:207], v[146:147], v[74:75], v[218:219]
	v_pk_fma_f32 v[204:205], v[144:145], v[72:73], v[216:217]
	global_store_dwordx4 v[220:221], v[156:159], off
	v_mul_f32_e32 v218, v157, v157
	v_mul_f32_e32 v219, v159, v159
	v_pk_mul_f32 v[144:145], v[102:103], v[158:159]
	v_pk_mul_f32 v[146:147], v[100:101], v[156:157]
	v_mul_f32_e32 v157, v153, v153
	v_mul_f32_e32 v159, v155, v155
	v_lshl_add_u64 v[222:223], v[222:223], 1, s[14:15]
	v_mul_f32_e32 v225, v149, v149
	v_mul_f32_e32 v226, v151, v151
	v_fmac_f32_e32 v218, v156, v156
	v_fmac_f32_e32 v219, v158, v158
	v_cvt_pk_bf16_f32 v248, v146, v147
	v_cvt_pk_bf16_f32 v249, v144, v145
	v_fmac_f32_e32 v157, v152, v152
	v_fmac_f32_e32 v159, v154, v154
	v_mul_f32_e32 v227, v205, v205
	v_mul_f32_e32 v228, v207, v207
	v_fmac_f32_e32 v225, v148, v148
	v_fmac_f32_e32 v226, v150, v150
	v_add_f32_e32 v156, v218, v219
	global_store_dwordx4 v[220:221], v[152:155], off offset:64
	v_add_f32_e32 v146, v157, v159
	v_pk_mul_f32 v[208:209], v[90:91], v[154:155]
	v_pk_mul_f32 v[210:211], v[88:89], v[152:153]
	v_fmac_f32_e32 v227, v204, v204
	v_fmac_f32_e32 v228, v206, v206
	v_cvt_pk_bf16_f32 v250, v210, v211
	v_cvt_pk_bf16_f32 v251, v208, v209
	v_add_f32_e32 v147, v225, v226
	v_add_f32_e32 v146, v156, v146
	v_add_f32_e32 v152, v227, v228
	v_mbcnt_lo_u32_b32 v252, -1, 0
	v_mbcnt_hi_u32_b32 v252, -1, v252
	v_bfe_u32 v252, v252, 4, 1
	v_mul_u32_u24_e32 v252, 24, v252
	v_mov_b32_e32 v253, 0
	v_permlane16_swap_b32 v248, v250
	v_permlane16_swap_b32 v249, v251
	v_lshl_add_u64 v[252:253], v[222:223], 0, v[252:253]
	global_store_dwordx4 v[252:253], v[248:251], off
	global_store_dwordx4 v[220:221], v[148:151], off offset:512
	v_add_f32_e32 v144, v146, v147
	v_lshlrev_b32_e32 v203, 2, v203
	v_add_f32_e32 v146, v144, v152
	ds_bpermute_b32 v147, v203, v146
	v_pk_mul_f32 v[212:213], v[82:83], v[150:151]
	v_pk_mul_f32 v[214:215], v[80:81], v[148:149]
	v_pk_mul_f32 v[216:217], v[66:67], v[206:207]
	v_cvt_pk_bf16_f32 v248, v214, v215
	v_cvt_pk_bf16_f32 v249, v212, v213
	global_store_dwordx4 v[220:221], v[204:207], off offset:576
	v_xor_b32_e32 v145, 32, v202
	v_cmp_lt_i32_e64 s[4:5], v145, v224
	s_waitcnt lgkmcnt(0)
	v_add_f32_e32 v144, v146, v147
	v_pk_mul_f32 v[146:147], v[64:65], v[204:205]
	v_cndmask_b32_e64 v145, v202, v145, s[4:5]
	v_lshlrev_b32_e32 v150, 2, v145
	ds_bpermute_b32 v145, v150, v144
	v_cvt_pk_bf16_f32 v250, v146, v147
	v_cvt_pk_bf16_f32 v251, v216, v217
	v_mbcnt_lo_u32_b32 v252, -1, 0
	v_mbcnt_hi_u32_b32 v252, -1, v252
	v_bfe_u32 v252, v252, 4, 1
	v_mul_u32_u24_e32 v252, 24, v252
	v_mov_b32_e32 v253, 0
	v_permlane16_swap_b32 v248, v250
	v_permlane16_swap_b32 v249, v251
	v_lshl_add_u64 v[252:253], v[222:223], 0, v[252:253]
	global_store_dwordx4 v[252:253], v[248:251], off offset:256
	s_and_saveexec_b64 s[4:5], vcc
	s_cbranch_execz .LBB0_1309
	s_waitcnt lgkmcnt(0)
	v_add_f32_e32 v144, v144, v145
	v_mul_f32_e32 v144, 0x4b800000, v144
	v_trunc_f32_e32 v144, v144
	v_mul_f32_e32 v145, 0x2f800000, v144
	v_floor_f32_e32 v145, v145
	v_fmac_f32_e32 v144, 0xcf800000, v145
	v_cvt_u32_f32_e32 v144, v144
	v_cvt_u32_f32_e32 v145, v145
	v_mov_b32_e32 v230, v144
	v_mov_b32_e32 v231, v145
	v_lshl_add_u64 v[246:247], v[192:193], 3, s[18:19]
; __device__ __forceinline__ unsigned cvt_pk_bf16(float lo, float hi) { unsigned r; asm volatile("v_cvt_pk_bf16_f32 %0, %1, %2" : "=v"(r) : "v"(lo), "v"(hi)); return r; }
;     __device__ __forceinline__ void operator()(const f32x4 (&acc)[2][2][4][2], const Unit& u, int wr, int wc, int fr_, int fq_) const {
;     ...
;             for (int m = 0; m < 2; ++m) { const int row = row0 + ai * HALF + (2 * mh + m) * 16; const size_t off = (size_t)row * ldc + col0; float ss = 0.f;
; #pragma unroll
;                 for (int bj = 0; bj < 2; ++bj)
; #pragma unroll
;                     for (int n = 0; n < 2; ++n) { const f32x4 o = bs[m][bj][n] + gv[bj][n] * acc[ai][bj][2 * mh + m][n]; *(f32x4*)(out + off + bj * HALF + n * 16) = o;
;                         if constexpr (EMIT) { ss += (o[0] * o[0] + o[1] * o[1]) + (o[2] * o[2] + o[3] * o[3]); const f32x4 y = o * gm[bj][n];
;                             typedef unsigned u32x2_t __attribute__((ext_vector_type(2))); u32x2_t w; w.x = cvt_pk_bf16(y[0], y[1]); w.y = cvt_pk_bf16(y[2], y[3]); *(u32x2_t*)(A2 + off + bj * HALF + n * 16) = w; } }
;                 if constexpr (EMIT) { ss += __shfl_xor(ss, 16); ss += __shfl_xor(ss, 32); if (fq == 0) atomicAdd(ssq + row, (unsigned long long)(ss * 16777216.0f)); } }
.LBB0_1309:
	s_or_b64 exec, exec, s[4:5]
	v_pk_fma_f32 v[142:143], v[142:143], v[106:107], v[174:175]
	v_pk_fma_f32 v[140:141], v[140:141], v[104:105], v[172:173]
	s_waitcnt lgkmcnt(0)
	v_lshlrev_b64 v[144:145], 11, v[194:195]
	v_mul_f32_e32 v146, v141, v141
	v_mul_f32_e32 v147, v143, v143
	v_lshl_add_u64 v[144:145], v[144:145], 0, v[188:189]
	global_store_dwordx4 v[196:197], v[140:143], off
	v_fmac_f32_e32 v146, v140, v140
	v_fmac_f32_e32 v147, v142, v142
	v_pk_mul_f32 v[142:143], v[102:103], v[142:143]
	v_pk_mul_f32 v[140:141], v[100:101], v[140:141]
	v_pk_fma_f32 v[136:137], v[136:137], v[92:93], v[168:169]
	v_cvt_pk_bf16_f32 v248, v140, v141
	v_cvt_pk_bf16_f32 v249, v142, v143
	v_lshl_add_u64 v[142:143], v[144:145], 1, s[14:15]
	v_pk_fma_f32 v[138:139], v[138:139], v[94:95], v[170:171]
	v_mul_f32_e32 v140, v137, v137
	global_store_dwordx4 v[196:197], v[136:139], off offset:64
	v_fmac_f32_e32 v140, v136, v136
	v_mul_f32_e32 v141, v139, v139
	v_pk_mul_f32 v[136:137], v[88:89], v[136:137]
	v_fmac_f32_e32 v141, v138, v138
	v_pk_mul_f32 v[138:139], v[90:91], v[138:139]
	v_cvt_pk_bf16_f32 v250, v136, v137
	v_pk_fma_f32 v[134:135], v[134:135], v[86:87], v[166:167]
	v_cvt_pk_bf16_f32 v251, v138, v139
	v_pk_fma_f32 v[132:133], v[132:133], v[84:85], v[164:165]
	v_mbcnt_lo_u32_b32 v252, -1, 0
	v_mbcnt_hi_u32_b32 v252, -1, v252
	v_bfe_u32 v252, v252, 4, 1
	v_mul_u32_u24_e32 v252, 24, v252
	v_mov_b32_e32 v253, 0
	v_permlane16_swap_b32 v248, v250
	v_permlane16_swap_b32 v249, v251
	v_lshl_add_u64 v[252:253], v[142:143], 0, v[252:253]
	global_store_dwordx4 v[252:253], v[248:251], off
	v_mul_f32_e32 v136, v133, v133
	v_mul_f32_e32 v137, v135, v135
	v_add_f32_e32 v146, v146, v147
	v_add_f32_e32 v140, v140, v141
	v_fmac_f32_e32 v136, v132, v132
	v_fmac_f32_e32 v137, v134, v134
	v_add_f32_e32 v140, v146, v140
	global_store_dwordx4 v[196:197], v[132:135], off offset:512
	v_add_f32_e32 v136, v136, v137
	v_add_f32_e32 v137, v140, v136
	v_pk_mul_f32 v[132:133], v[80:81], v[132:133]
	v_pk_mul_f32 v[134:135], v[82:83], v[134:135]
	v_cvt_pk_bf16_f32 v248, v132, v133
	v_pk_fma_f32 v[132:133], v[130:131], v[74:75], v[162:163]
	v_pk_fma_f32 v[130:131], v[128:129], v[72:73], v[160:161]
	v_mul_f32_e32 v129, v133, v133
	v_mul_f32_e32 v128, v131, v131
	v_fmac_f32_e32 v128, v130, v130
	v_fmac_f32_e32 v129, v132, v132
	v_add_f32_e32 v128, v128, v129
	v_add_f32_e32 v128, v137, v128
	ds_bpermute_b32 v129, v203, v128
	v_cvt_pk_bf16_f32 v249, v134, v135
	global_store_dwordx4 v[196:197], v[130:133], off offset:576
	s_waitcnt lgkmcnt(0)
	v_add_f32_e32 v128, v128, v129
	ds_bpermute_b32 v129, v150, v128
	v_pk_mul_f32 v[130:131], v[64:65], v[130:131]
	v_pk_mul_f32 v[132:133], v[66:67], v[132:133]
	v_cvt_pk_bf16_f32 v250, v130, v131
	s_nop 0
	v_cvt_pk_bf16_f32 v251, v132, v133
	v_mbcnt_lo_u32_b32 v252, -1, 0
	v_mbcnt_hi_u32_b32 v252, -1, v252
	v_bfe_u32 v252, v252, 4, 1
	v_mul_u32_u24_e32 v252, 24, v252
	v_mov_b32_e32 v253, 0
	v_permlane16_swap_b32 v248, v250
	v_permlane16_swap_b32 v249, v251
	v_lshl_add_u64 v[252:253], v[142:143], 0, v[252:253]
	global_store_dwordx4 v[252:253], v[248:251], off offset:256
	s_and_saveexec_b64 s[4:5], vcc
	s_cbranch_execz .LBB0_1311
	s_waitcnt lgkmcnt(0)
	v_add_f32_e32 v128, v128, v129
	v_mul_f32_e32 v128, 0x4b800000, v128
	v_trunc_f32_e32 v128, v128
	v_mul_f32_e32 v129, 0x2f800000, v128
	v_floor_f32_e32 v129, v129
	v_fmac_f32_e32 v128, 0xcf800000, v129
	v_cvt_u32_f32_e32 v128, v128
	v_cvt_u32_f32_e32 v129, v129
	v_mov_b32_e32 v232, v128
	v_mov_b32_e32 v233, v129
.LBB0_1311:
	s_or_b64 exec, exec, s[4:5]
	v_or_b32_e32 v148, 32, v192
	v_ashrrev_i32_e32 v149, 31, v148
	s_waitcnt lgkmcnt(0)
	v_lshlrev_b64 v[128:129], 13, v[148:149]
	v_lshl_add_u64 v[168:169], v[190:191], 0, v[128:129]
	global_load_dwordx4 v[152:155], v[168:169], off
	global_load_dwordx4 v[156:159], v[168:169], off offset:64
	global_load_dwordx4 v[160:163], v[168:169], off offset:512
	global_load_dwordx4 v[164:167], v[168:169], off offset:576
	v_or_b32_e32 v144, 48, v192
	v_ashrrev_i32_e32 v145, 31, v144
	v_lshlrev_b64 v[128:129], 13, v[144:145]
	v_lshl_add_u64 v[146:147], v[190:191], 0, v[128:129]
	global_load_dwordx4 v[140:143], v[146:147], off
	global_load_dwordx4 v[136:139], v[146:147], off offset:64
	global_load_dwordx4 v[132:135], v[146:147], off offset:512
	global_load_dwordx4 v[128:131], v[146:147], off offset:576
	v_lshlrev_b64 v[170:171], 11, v[148:149]
	v_lshl_add_u64 v[170:171], v[170:171], 0, v[188:189]
	v_lshl_add_u64 v[170:171], v[170:171], 1, s[14:15]
	s_waitcnt vmcnt(0) lgkmcnt(0)
; __device__ __forceinline__ unsigned cvt_pk_bf16(float lo, float hi) { unsigned r; asm volatile("v_cvt_pk_bf16_f32 %0, %1, %2" : "=v"(r) : "v"(lo), "v"(hi)); return r; }
;     __device__ __forceinline__ void operator()(const f32x4 (&acc)[2][2][4][2], const Unit& u, int wr, int wc, int fr_, int fq_) const {
;     ...
;             for (int m = 0; m < 2; ++m) { const int row = row0 + ai * HALF + (2 * mh + m) * 16; const size_t off = (size_t)row * ldc + col0; float ss = 0.f;
; #pragma unroll
;                 for (int bj = 0; bj < 2; ++bj)
; #pragma unroll
;                     for (int n = 0; n < 2; ++n) { const f32x4 o = bs[m][bj][n] + gv[bj][n] * acc[ai][bj][2 * mh + m][n]; *(f32x4*)(out + off + bj * HALF + n * 16) = o;
;                         if constexpr (EMIT) { ss += (o[0] * o[0] + o[1] * o[1]) + (o[2] * o[2] + o[3] * o[3]); const f32x4 y = o * gm[bj][n];
;                             typedef unsigned u32x2_t __attribute__((ext_vector_type(2))); u32x2_t w; w.x = cvt_pk_bf16(y[0], y[1]); w.y = cvt_pk_bf16(y[2], y[3]); *(u32x2_t*)(A2 + off + bj * HALF + n * 16) = w; } }
;                 if constexpr (EMIT) { ss += __shfl_xor(ss, 16); ss += __shfl_xor(ss, 32); if (fq == 0) atomicAdd(ssq + row, (unsigned long long)(ss * 16777216.0f)); } }
	v_pk_fma_f32 v[126:127], v[126:127], v[106:107], v[154:155]
	v_pk_fma_f32 v[124:125], v[124:125], v[104:105], v[152:153]
	v_pk_fma_f32 v[122:123], v[122:123], v[94:95], v[158:159]
	v_pk_fma_f32 v[120:121], v[120:121], v[92:93], v[156:157]
	v_pk_fma_f32 v[118:119], v[118:119], v[86:87], v[162:163]
	v_pk_fma_f32 v[116:117], v[116:117], v[84:85], v[160:161]
	v_pk_fma_f32 v[154:155], v[114:115], v[74:75], v[166:167]
	v_pk_fma_f32 v[152:153], v[112:113], v[72:73], v[164:165]
	global_store_dwordx4 v[168:169], v[124:127], off
	v_mul_f32_e32 v151, v125, v125
	v_mul_f32_e32 v164, v127, v127
	v_pk_mul_f32 v[112:113], v[102:103], v[126:127]
	v_pk_mul_f32 v[114:115], v[100:101], v[124:125]
	v_mul_f32_e32 v125, v121, v121
	v_mul_f32_e32 v127, v123, v123
	v_mul_f32_e32 v165, v117, v117
	v_mul_f32_e32 v166, v119, v119
	v_fmac_f32_e32 v151, v124, v124
	v_fmac_f32_e32 v164, v126, v126
	v_cvt_pk_bf16_f32 v248, v114, v115
	v_cvt_pk_bf16_f32 v249, v112, v113
	v_fmac_f32_e32 v125, v120, v120
	v_fmac_f32_e32 v127, v122, v122
	v_mul_f32_e32 v167, v153, v153
	v_mul_f32_e32 v172, v155, v155
	v_fmac_f32_e32 v165, v116, v116
	v_fmac_f32_e32 v166, v118, v118
	v_add_f32_e32 v124, v151, v164
	global_store_dwordx4 v[168:169], v[120:123], off offset:64
	v_add_f32_e32 v114, v125, v127
	v_pk_mul_f32 v[156:157], v[90:91], v[122:123]
	v_pk_mul_f32 v[158:159], v[88:89], v[120:121]
	v_fmac_f32_e32 v167, v152, v152
	v_fmac_f32_e32 v172, v154, v154
	v_cvt_pk_bf16_f32 v250, v158, v159
	v_cvt_pk_bf16_f32 v251, v156, v157
	v_add_f32_e32 v115, v165, v166
	v_add_f32_e32 v114, v124, v114
	v_mbcnt_lo_u32_b32 v252, -1, 0
	v_mbcnt_hi_u32_b32 v252, -1, v252
	v_bfe_u32 v252, v252, 4, 1
	v_mul_u32_u24_e32 v252, 24, v252
	v_mov_b32_e32 v253, 0
	v_permlane16_swap_b32 v248, v250
	v_permlane16_swap_b32 v249, v251
	v_lshl_add_u64 v[252:253], v[170:171], 0, v[252:253]
	global_store_dwordx4 v[252:253], v[248:251], off
	global_store_dwordx4 v[168:169], v[116:119], off offset:512
	v_add_f32_e32 v113, v114, v115
	v_add_f32_e32 v114, v167, v172
	v_pk_mul_f32 v[162:163], v[80:81], v[116:117]
	v_add_f32_e32 v116, v113, v114
	ds_bpermute_b32 v117, v203, v116
	v_pk_mul_f32 v[160:161], v[82:83], v[118:119]
	v_cvt_pk_bf16_f32 v248, v162, v163
	v_pk_mul_f32 v[114:115], v[66:67], v[154:155]
	v_cvt_pk_bf16_f32 v249, v160, v161
	global_store_dwordx4 v[168:169], v[152:155], off offset:576
	s_waitcnt lgkmcnt(0)
	v_add_f32_e32 v112, v116, v117
	ds_bpermute_b32 v113, v150, v112
	v_pk_mul_f32 v[116:117], v[64:65], v[152:153]
	s_nop 0
	v_cvt_pk_bf16_f32 v250, v116, v117
	v_cvt_pk_bf16_f32 v251, v114, v115
	v_mbcnt_lo_u32_b32 v252, -1, 0
	v_mbcnt_hi_u32_b32 v252, -1, v252
	v_bfe_u32 v252, v252, 4, 1
	v_mul_u32_u24_e32 v252, 24, v252
	v_mov_b32_e32 v253, 0
	v_permlane16_swap_b32 v248, v250
	v_permlane16_swap_b32 v249, v251
	v_lshl_add_u64 v[252:253], v[170:171], 0, v[252:253]
	global_store_dwordx4 v[252:253], v[248:251], off offset:256
	s_and_saveexec_b64 s[4:5], vcc
	s_cbranch_execz .LBB0_1313
	s_waitcnt lgkmcnt(0)
	v_add_f32_e32 v112, v112, v113
	v_mul_f32_e32 v112, 0x4b800000, v112
	v_trunc_f32_e32 v112, v112
	v_mul_f32_e32 v113, 0x2f800000, v112
	v_floor_f32_e32 v113, v113
	v_fmac_f32_e32 v112, 0xcf800000, v113
	v_cvt_u32_f32_e32 v112, v112
	v_cvt_u32_f32_e32 v113, v113
	v_mov_b32_e32 v234, v112
	v_mov_b32_e32 v235, v113
.LBB0_1313:
	s_or_b64 exec, exec, s[4:5]
	v_pk_fma_f32 v[110:111], v[110:111], v[106:107], v[142:143]
	v_pk_fma_f32 v[108:109], v[108:109], v[104:105], v[140:141]
	s_waitcnt lgkmcnt(0)
	v_lshlrev_b64 v[112:113], 11, v[144:145]
	v_mul_f32_e32 v114, v109, v109
	v_mul_f32_e32 v115, v111, v111
	v_lshl_add_u64 v[112:113], v[112:113], 0, v[188:189]
	global_store_dwordx4 v[146:147], v[108:111], off
	v_fmac_f32_e32 v114, v108, v108
	v_fmac_f32_e32 v115, v110, v110
	v_pk_mul_f32 v[110:111], v[102:103], v[110:111]
	v_pk_mul_f32 v[108:109], v[100:101], v[108:109]
	v_pk_fma_f32 v[96:97], v[96:97], v[92:93], v[136:137]
	v_cvt_pk_bf16_f32 v248, v108, v109
	v_cvt_pk_bf16_f32 v249, v110, v111
	v_lshl_add_u64 v[110:111], v[112:113], 1, s[14:15]
	v_pk_fma_f32 v[98:99], v[98:99], v[94:95], v[138:139]
	v_mul_f32_e32 v108, v97, v97
	global_store_dwordx4 v[146:147], v[96:99], off offset:64
	v_fmac_f32_e32 v108, v96, v96
	v_mul_f32_e32 v109, v99, v99
	v_pk_mul_f32 v[96:97], v[88:89], v[96:97]
	v_fmac_f32_e32 v109, v98, v98
	v_pk_mul_f32 v[98:99], v[90:91], v[98:99]
	v_cvt_pk_bf16_f32 v250, v96, v97
	v_pk_fma_f32 v[78:79], v[78:79], v[86:87], v[134:135]
	v_cvt_pk_bf16_f32 v251, v98, v99
	v_pk_fma_f32 v[76:77], v[76:77], v[84:85], v[132:133]
	v_mbcnt_lo_u32_b32 v252, -1, 0
	v_mbcnt_hi_u32_b32 v252, -1, v252
	v_bfe_u32 v252, v252, 4, 1
	v_mul_u32_u24_e32 v252, 24, v252
	v_mov_b32_e32 v253, 0
	v_permlane16_swap_b32 v248, v250
	v_permlane16_swap_b32 v249, v251
	v_lshl_add_u64 v[252:253], v[110:111], 0, v[252:253]
	global_store_dwordx4 v[252:253], v[248:251], off
	v_mul_f32_e32 v96, v77, v77
	v_mul_f32_e32 v97, v79, v79
	v_add_f32_e32 v114, v114, v115
	v_add_f32_e32 v108, v108, v109
	v_fmac_f32_e32 v96, v76, v76
	v_fmac_f32_e32 v97, v78, v78
	v_add_f32_e32 v108, v114, v108
	global_store_dwordx4 v[146:147], v[76:79], off offset:512
	v_add_f32_e32 v96, v96, v97
	v_add_f32_e32 v99, v108, v96
	v_pk_mul_f32 v[76:77], v[80:81], v[76:77]
	v_pk_mul_f32 v[96:97], v[82:83], v[78:79]
	v_cvt_pk_bf16_f32 v248, v76, v77
	v_pk_fma_f32 v[78:79], v[70:71], v[74:75], v[130:131]
	v_pk_fma_f32 v[76:77], v[68:69], v[72:73], v[128:129]
	v_mul_f32_e32 v69, v79, v79
	v_mul_f32_e32 v68, v77, v77
	v_fmac_f32_e32 v68, v76, v76
	v_fmac_f32_e32 v69, v78, v78
	v_add_f32_e32 v68, v68, v69
	v_add_f32_e32 v68, v99, v68
	ds_bpermute_b32 v69, v203, v68
	v_cvt_pk_bf16_f32 v249, v96, v97
	global_store_dwordx4 v[146:147], v[76:79], off offset:576
	v_pk_mul_f32 v[70:71], v[66:67], v[78:79]
	s_waitcnt lgkmcnt(0)
	v_add_f32_e32 v68, v68, v69
	ds_bpermute_b32 v69, v150, v68
	v_pk_mul_f32 v[76:77], v[64:65], v[76:77]
	s_nop 0
	v_cvt_pk_bf16_f32 v250, v76, v77
	v_cvt_pk_bf16_f32 v251, v70, v71
	v_mbcnt_lo_u32_b32 v252, -1, 0
	v_mbcnt_hi_u32_b32 v252, -1, v252
	v_bfe_u32 v252, v252, 4, 1
	v_mul_u32_u24_e32 v252, 24, v252
	v_mov_b32_e32 v253, 0
	v_permlane16_swap_b32 v248, v250
	v_permlane16_swap_b32 v249, v251
	v_lshl_add_u64 v[252:253], v[110:111], 0, v[252:253]
	global_store_dwordx4 v[252:253], v[248:251], off offset:256
	s_and_saveexec_b64 s[4:5], vcc
	s_cbranch_execz .LBB0_1315
	s_waitcnt lgkmcnt(0)
	v_add_f32_e32 v68, v68, v69
	v_mul_f32_e32 v68, 0x4b800000, v68
	v_trunc_f32_e32 v68, v68
	v_mul_f32_e32 v69, 0x2f800000, v68
	v_floor_f32_e32 v69, v69
	v_fmac_f32_e32 v68, 0xcf800000, v69
	v_cvt_u32_f32_e32 v68, v68
	v_cvt_u32_f32_e32 v69, v69
	v_mov_b32_e32 v236, v68
	v_mov_b32_e32 v237, v69
; __device__ __forceinline__ unsigned cvt_pk_bf16(float lo, float hi) { unsigned r; asm volatile("v_cvt_pk_bf16_f32 %0, %1, %2" : "=v"(r) : "v"(lo), "v"(hi)); return r; }
;     __device__ __forceinline__ void operator()(const f32x4 (&acc)[2][2][4][2], const Unit& u, int wr, int wc, int fr_, int fq_) const {
;     ...
;             for (int m = 0; m < 2; ++m) { const size_t off = (size_t)(row0 + ai * HALF + (2 * mh + m) * 16) * ldc + col0;
; #pragma unroll
;                 for (int bj = 0; bj < 2; ++bj)
; #pragma unroll
;                     for (int n = 0; n < 2; ++n) bs[m][bj][n] = *(const f32x4*)(base + off + bj * HALF + n * 16); }
;             asm volatile("" ::: "memory");
; #pragma unroll
;             for (int m = 0; m < 2; ++m) { const int row = row0 + ai * HALF + (2 * mh + m) * 16; const size_t off = (size_t)row * ldc + col0; float ss = 0.f;
; #pragma unroll
;                 for (int bj = 0; bj < 2; ++bj)
; #pragma unroll
;                     for (int n = 0; n < 2; ++n) { const f32x4 o = bs[m][bj][n] + gv[bj][n] * acc[ai][bj][2 * mh + m][n]; *(f32x4*)(out + off + bj * HALF + n * 16) = o;
;                         if constexpr (EMIT) { ss += (o[0] * o[0] + o[1] * o[1]) + (o[2] * o[2] + o[3] * o[3]); const f32x4 y = o * gm[bj][n];
;                             typedef unsigned u32x2_t __attribute__((ext_vector_type(2))); u32x2_t w; w.x = cvt_pk_bf16(y[0], y[1]); w.y = cvt_pk_bf16(y[2], y[3]); *(u32x2_t*)(A2 + off + bj * HALF + n * 16) = w; } }
;                 if constexpr (EMIT) { ss += __shfl_xor(ss, 16); ss += __shfl_xor(ss, 32); if (fq == 0) atomicAdd(ssq + row, (unsigned long long)(ss * 16777216.0f)); } }
.LBB0_1315:
	s_or_b64 exec, exec, s[4:5]
	v_add_u32_e32 v116, 0x80, v192
	v_ashrrev_i32_e32 v117, 31, v116
	s_waitcnt lgkmcnt(0)
	v_lshlrev_b64 v[68:69], 13, v[116:117]
	v_lshl_add_u64 v[134:135], v[190:191], 0, v[68:69]
	global_load_dwordx4 v[118:121], v[134:135], off
	global_load_dwordx4 v[122:125], v[134:135], off offset:64
	global_load_dwordx4 v[126:129], v[134:135], off offset:512
	global_load_dwordx4 v[130:133], v[134:135], off offset:576
	v_add_u32_e32 v112, 0x90, v192
	v_ashrrev_i32_e32 v113, 31, v112
	v_lshlrev_b64 v[68:69], 13, v[112:113]
	v_lshl_add_u64 v[114:115], v[190:191], 0, v[68:69]
	global_load_dwordx4 v[108:111], v[114:115], off
	global_load_dwordx4 v[96:99], v[114:115], off offset:64
	global_load_dwordx4 v[76:79], v[114:115], off offset:512
	global_load_dwordx4 v[68:71], v[114:115], off offset:576
	v_lshlrev_b64 v[136:137], 11, v[116:117]
	v_lshl_add_u64 v[136:137], v[136:137], 0, v[188:189]
	v_lshl_add_u64 v[136:137], v[136:137], 1, s[14:15]
	s_waitcnt vmcnt(0) lgkmcnt(0)
	v_pk_fma_f32 v[62:63], v[62:63], v[106:107], v[120:121]
	v_pk_fma_f32 v[60:61], v[60:61], v[104:105], v[118:119]
	v_pk_fma_f32 v[58:59], v[58:59], v[94:95], v[124:125]
	v_pk_fma_f32 v[56:57], v[56:57], v[92:93], v[122:123]
	v_pk_fma_f32 v[54:55], v[54:55], v[86:87], v[128:129]
	v_pk_fma_f32 v[52:53], v[52:53], v[84:85], v[126:127]
	v_pk_fma_f32 v[120:121], v[50:51], v[74:75], v[132:133]
	v_pk_fma_f32 v[118:119], v[48:49], v[72:73], v[130:131]
	global_store_dwordx4 v[134:135], v[60:63], off
	v_mul_f32_e32 v130, v61, v61
	v_mul_f32_e32 v131, v63, v63
	v_pk_mul_f32 v[48:49], v[102:103], v[62:63]
	v_pk_mul_f32 v[50:51], v[100:101], v[60:61]
	v_mul_f32_e32 v61, v57, v57
	v_mul_f32_e32 v63, v59, v59
	v_mul_f32_e32 v132, v53, v53
	v_mul_f32_e32 v133, v55, v55
	v_fmac_f32_e32 v130, v60, v60
	v_fmac_f32_e32 v131, v62, v62
	v_cvt_pk_bf16_f32 v248, v50, v51
	v_cvt_pk_bf16_f32 v249, v48, v49
	v_fmac_f32_e32 v61, v56, v56
	v_fmac_f32_e32 v63, v58, v58
	v_mul_f32_e32 v138, v119, v119
	v_mul_f32_e32 v139, v121, v121
	v_fmac_f32_e32 v132, v52, v52
	v_fmac_f32_e32 v133, v54, v54
	v_add_f32_e32 v60, v130, v131
	global_store_dwordx4 v[134:135], v[56:59], off offset:64
	v_add_f32_e32 v50, v61, v63
	v_pk_mul_f32 v[122:123], v[90:91], v[58:59]
	v_pk_mul_f32 v[124:125], v[88:89], v[56:57]
	v_fmac_f32_e32 v138, v118, v118
	v_fmac_f32_e32 v139, v120, v120
	v_cvt_pk_bf16_f32 v250, v124, v125
	v_cvt_pk_bf16_f32 v251, v122, v123
	v_add_f32_e32 v51, v132, v133
	v_add_f32_e32 v50, v60, v50
	v_mbcnt_lo_u32_b32 v252, -1, 0
	v_mbcnt_hi_u32_b32 v252, -1, v252
	v_bfe_u32 v252, v252, 4, 1
	v_mul_u32_u24_e32 v252, 24, v252
	v_mov_b32_e32 v253, 0
	v_permlane16_swap_b32 v248, v250
	v_permlane16_swap_b32 v249, v251
	v_lshl_add_u64 v[252:253], v[136:137], 0, v[252:253]
	global_store_dwordx4 v[252:253], v[248:251], off
	global_store_dwordx4 v[134:135], v[52:55], off offset:512
	v_add_f32_e32 v49, v50, v51
	v_add_f32_e32 v50, v138, v139
	v_pk_mul_f32 v[128:129], v[80:81], v[52:53]
	v_add_f32_e32 v52, v49, v50
	ds_bpermute_b32 v53, v203, v52
	v_pk_mul_f32 v[126:127], v[82:83], v[54:55]
	v_cvt_pk_bf16_f32 v248, v128, v129
	v_pk_mul_f32 v[50:51], v[66:67], v[120:121]
	v_cvt_pk_bf16_f32 v249, v126, v127
	global_store_dwordx4 v[134:135], v[118:121], off offset:576
	s_waitcnt lgkmcnt(0)
	v_add_f32_e32 v48, v52, v53
	ds_bpermute_b32 v49, v150, v48
	v_pk_mul_f32 v[52:53], v[64:65], v[118:119]
	s_nop 0
	v_cvt_pk_bf16_f32 v250, v52, v53
	v_cvt_pk_bf16_f32 v251, v50, v51
	v_mbcnt_lo_u32_b32 v252, -1, 0
	v_mbcnt_hi_u32_b32 v252, -1, v252
	v_bfe_u32 v252, v252, 4, 1
	v_mul_u32_u24_e32 v252, 24, v252
	v_mov_b32_e32 v253, 0
	v_permlane16_swap_b32 v248, v250
	v_permlane16_swap_b32 v249, v251
	v_lshl_add_u64 v[252:253], v[136:137], 0, v[252:253]
	global_store_dwordx4 v[252:253], v[248:251], off offset:256
	s_and_saveexec_b64 s[4:5], vcc
	s_cbranch_execz .LBB0_1317
	s_waitcnt lgkmcnt(0)
	v_add_f32_e32 v48, v48, v49
	v_mul_f32_e32 v48, 0x4b800000, v48
	v_trunc_f32_e32 v48, v48
	v_mul_f32_e32 v49, 0x2f800000, v48
	v_floor_f32_e32 v49, v49
	v_fmac_f32_e32 v48, 0xcf800000, v49
	v_cvt_u32_f32_e32 v48, v48
	v_cvt_u32_f32_e32 v49, v49
	v_mov_b32_e32 v238, v48
	v_mov_b32_e32 v239, v49
.LBB0_1317:
	s_or_b64 exec, exec, s[4:5]
	v_pk_fma_f32 v[46:47], v[46:47], v[106:107], v[110:111]
	v_pk_fma_f32 v[44:45], v[44:45], v[104:105], v[108:109]
	s_waitcnt lgkmcnt(0)
	v_lshlrev_b64 v[48:49], 11, v[112:113]
	v_mul_f32_e32 v50, v45, v45
	v_mul_f32_e32 v51, v47, v47
	v_lshl_add_u64 v[48:49], v[48:49], 0, v[188:189]
	global_store_dwordx4 v[114:115], v[44:47], off
	v_fmac_f32_e32 v50, v44, v44
	v_fmac_f32_e32 v51, v46, v46
	v_pk_mul_f32 v[46:47], v[102:103], v[46:47]
	v_pk_mul_f32 v[44:45], v[100:101], v[44:45]
	v_pk_fma_f32 v[40:41], v[40:41], v[92:93], v[96:97]
	v_cvt_pk_bf16_f32 v248, v44, v45
	v_cvt_pk_bf16_f32 v249, v46, v47
	v_lshl_add_u64 v[46:47], v[48:49], 1, s[14:15]
	v_pk_fma_f32 v[42:43], v[42:43], v[94:95], v[98:99]
	v_mul_f32_e32 v44, v41, v41
	global_store_dwordx4 v[114:115], v[40:43], off offset:64
	v_fmac_f32_e32 v44, v40, v40
	v_mul_f32_e32 v45, v43, v43
	v_pk_mul_f32 v[40:41], v[88:89], v[40:41]
	v_fmac_f32_e32 v45, v42, v42
	v_pk_mul_f32 v[42:43], v[90:91], v[42:43]
	v_cvt_pk_bf16_f32 v250, v40, v41
	v_pk_fma_f32 v[38:39], v[38:39], v[86:87], v[78:79]
	v_cvt_pk_bf16_f32 v251, v42, v43
	v_pk_fma_f32 v[36:37], v[36:37], v[84:85], v[76:77]
	v_mbcnt_lo_u32_b32 v252, -1, 0
	v_mbcnt_hi_u32_b32 v252, -1, v252
	v_bfe_u32 v252, v252, 4, 1
	v_mul_u32_u24_e32 v252, 24, v252
	v_mov_b32_e32 v253, 0
	v_permlane16_swap_b32 v248, v250
	v_permlane16_swap_b32 v249, v251
	v_lshl_add_u64 v[252:253], v[46:47], 0, v[252:253]
	global_store_dwordx4 v[252:253], v[248:251], off
	v_mul_f32_e32 v40, v37, v37
	v_mul_f32_e32 v41, v39, v39
	v_add_f32_e32 v50, v50, v51
	v_add_f32_e32 v44, v44, v45
	v_fmac_f32_e32 v40, v36, v36
	v_fmac_f32_e32 v41, v38, v38
	v_add_f32_e32 v44, v50, v44
	global_store_dwordx4 v[114:115], v[36:39], off offset:512
	v_add_f32_e32 v40, v40, v41
	v_add_f32_e32 v41, v44, v40
	v_pk_mul_f32 v[36:37], v[80:81], v[36:37]
	v_pk_mul_f32 v[38:39], v[82:83], v[38:39]
	v_cvt_pk_bf16_f32 v248, v36, v37
	v_pk_fma_f32 v[36:37], v[34:35], v[74:75], v[70:71]
	v_pk_fma_f32 v[34:35], v[32:33], v[72:73], v[68:69]
	v_mul_f32_e32 v33, v37, v37
	v_mul_f32_e32 v32, v35, v35
	v_fmac_f32_e32 v32, v34, v34
	v_fmac_f32_e32 v33, v36, v36
	v_add_f32_e32 v32, v32, v33
	v_add_f32_e32 v32, v41, v32
	ds_bpermute_b32 v33, v203, v32
	v_cvt_pk_bf16_f32 v249, v38, v39
	global_store_dwordx4 v[114:115], v[34:37], off offset:576
	s_waitcnt lgkmcnt(0)
; __device__ __forceinline__ unsigned cvt_pk_bf16(float lo, float hi) { unsigned r; asm volatile("v_cvt_pk_bf16_f32 %0, %1, %2" : "=v"(r) : "v"(lo), "v"(hi)); return r; }
;     __device__ __forceinline__ void operator()(const f32x4 (&acc)[2][2][4][2], const Unit& u, int wr, int wc, int fr_, int fq_) const {
;     ...
;             for (int m = 0; m < 2; ++m) { const size_t off = (size_t)(row0 + ai * HALF + (2 * mh + m) * 16) * ldc + col0;
; #pragma unroll
;                 for (int bj = 0; bj < 2; ++bj)
; #pragma unroll
;                     for (int n = 0; n < 2; ++n) bs[m][bj][n] = *(const f32x4*)(base + off + bj * HALF + n * 16); }
;             asm volatile("" ::: "memory");
; #pragma unroll
;             for (int m = 0; m < 2; ++m) { const int row = row0 + ai * HALF + (2 * mh + m) * 16; const size_t off = (size_t)row * ldc + col0; float ss = 0.f;
; #pragma unroll
;                 for (int bj = 0; bj < 2; ++bj)
; #pragma unroll
;                     for (int n = 0; n < 2; ++n) { const f32x4 o = bs[m][bj][n] + gv[bj][n] * acc[ai][bj][2 * mh + m][n]; *(f32x4*)(out + off + bj * HALF + n * 16) = o;
;                         if constexpr (EMIT) { ss += (o[0] * o[0] + o[1] * o[1]) + (o[2] * o[2] + o[3] * o[3]); const f32x4 y = o * gm[bj][n];
;                             typedef unsigned u32x2_t __attribute__((ext_vector_type(2))); u32x2_t w; w.x = cvt_pk_bf16(y[0], y[1]); w.y = cvt_pk_bf16(y[2], y[3]); *(u32x2_t*)(A2 + off + bj * HALF + n * 16) = w; } }
;                 if constexpr (EMIT) { ss += __shfl_xor(ss, 16); ss += __shfl_xor(ss, 32); if (fq == 0) atomicAdd(ssq + row, (unsigned long long)(ss * 16777216.0f)); } }
	v_add_f32_e32 v32, v32, v33
	ds_bpermute_b32 v33, v150, v32
	v_pk_mul_f32 v[34:35], v[64:65], v[34:35]
	v_pk_mul_f32 v[36:37], v[66:67], v[36:37]
	v_cvt_pk_bf16_f32 v250, v34, v35
	s_nop 0
	v_cvt_pk_bf16_f32 v251, v36, v37
	v_mbcnt_lo_u32_b32 v252, -1, 0
	v_mbcnt_hi_u32_b32 v252, -1, v252
	v_bfe_u32 v252, v252, 4, 1
	v_mul_u32_u24_e32 v252, 24, v252
	v_mov_b32_e32 v253, 0
	v_permlane16_swap_b32 v248, v250
	v_permlane16_swap_b32 v249, v251
	v_lshl_add_u64 v[252:253], v[46:47], 0, v[252:253]
	global_store_dwordx4 v[252:253], v[248:251], off offset:256
	s_and_saveexec_b64 s[4:5], vcc
	s_cbranch_execz .LBB0_1319
	s_waitcnt lgkmcnt(0)
	v_add_f32_e32 v32, v32, v33
	v_mul_f32_e32 v32, 0x4b800000, v32
	v_trunc_f32_e32 v32, v32
	v_mul_f32_e32 v33, 0x2f800000, v32
	v_floor_f32_e32 v33, v33
	v_fmac_f32_e32 v32, 0xcf800000, v33
	v_cvt_u32_f32_e32 v32, v32
	v_cvt_u32_f32_e32 v33, v33
	v_mov_b32_e32 v240, v32
	v_mov_b32_e32 v241, v33
.LBB0_1319:
	s_or_b64 exec, exec, s[4:5]
	v_add_u32_e32 v52, 0xa0, v192
	v_ashrrev_i32_e32 v53, 31, v52
	s_waitcnt lgkmcnt(0)
	v_lshlrev_b64 v[32:33], 13, v[52:53]
	v_lshl_add_u64 v[62:63], v[190:191], 0, v[32:33]
	global_load_dwordx4 v[54:57], v[62:63], off
	global_load_dwordx4 v[58:61], v[62:63], off offset:64
	global_load_dwordx4 v[68:71], v[62:63], off offset:512
	global_load_dwordx4 v[76:79], v[62:63], off offset:576
	v_add_u32_e32 v48, 0xb0, v192
	v_ashrrev_i32_e32 v49, 31, v48
	v_lshlrev_b64 v[32:33], 13, v[48:49]
	v_lshl_add_u64 v[50:51], v[190:191], 0, v[32:33]
	global_load_dwordx4 v[44:47], v[50:51], off
	global_load_dwordx4 v[40:43], v[50:51], off offset:64
	global_load_dwordx4 v[36:39], v[50:51], off offset:512
	global_load_dwordx4 v[32:35], v[50:51], off offset:576
	v_lshlrev_b64 v[96:97], 11, v[52:53]
	v_lshl_add_u64 v[96:97], v[96:97], 0, v[188:189]
	v_lshl_add_u64 v[96:97], v[96:97], 1, s[14:15]
	s_waitcnt vmcnt(0) lgkmcnt(0)
	v_pk_fma_f32 v[30:31], v[30:31], v[106:107], v[56:57]
	v_pk_fma_f32 v[28:29], v[28:29], v[104:105], v[54:55]
	v_pk_fma_f32 v[26:27], v[26:27], v[94:95], v[60:61]
	v_pk_fma_f32 v[24:25], v[24:25], v[92:93], v[58:59]
	v_pk_fma_f32 v[22:23], v[22:23], v[86:87], v[70:71]
	v_pk_fma_f32 v[20:21], v[20:21], v[84:85], v[68:69]
	v_pk_fma_f32 v[56:57], v[18:19], v[74:75], v[78:79]
	v_pk_fma_f32 v[54:55], v[16:17], v[72:73], v[76:77]
	global_store_dwordx4 v[62:63], v[28:31], off
	v_mul_f32_e32 v76, v29, v29
	v_mul_f32_e32 v77, v31, v31
	v_pk_mul_f32 v[16:17], v[102:103], v[30:31]
	v_pk_mul_f32 v[18:19], v[100:101], v[28:29]
	v_mul_f32_e32 v29, v25, v25
	v_mul_f32_e32 v31, v27, v27
	v_mul_f32_e32 v78, v21, v21
	v_mul_f32_e32 v79, v23, v23
	v_fmac_f32_e32 v76, v28, v28
	v_fmac_f32_e32 v77, v30, v30
	v_cvt_pk_bf16_f32 v248, v18, v19
	v_cvt_pk_bf16_f32 v249, v16, v17
	v_fmac_f32_e32 v29, v24, v24
	v_fmac_f32_e32 v31, v26, v26
	v_mul_f32_e32 v98, v55, v55
	v_mul_f32_e32 v99, v57, v57
	v_fmac_f32_e32 v78, v20, v20
	v_fmac_f32_e32 v79, v22, v22
	v_add_f32_e32 v28, v76, v77
	global_store_dwordx4 v[62:63], v[24:27], off offset:64
	v_add_f32_e32 v18, v29, v31
	v_pk_mul_f32 v[58:59], v[90:91], v[26:27]
	v_pk_mul_f32 v[60:61], v[88:89], v[24:25]
	v_fmac_f32_e32 v98, v54, v54
	v_fmac_f32_e32 v99, v56, v56
	v_cvt_pk_bf16_f32 v250, v60, v61
	v_cvt_pk_bf16_f32 v251, v58, v59
	v_add_f32_e32 v19, v78, v79
	v_add_f32_e32 v18, v28, v18
	v_mbcnt_lo_u32_b32 v252, -1, 0
	v_mbcnt_hi_u32_b32 v252, -1, v252
	v_bfe_u32 v252, v252, 4, 1
	v_mul_u32_u24_e32 v252, 24, v252
	v_mov_b32_e32 v253, 0
	v_permlane16_swap_b32 v248, v250
	v_permlane16_swap_b32 v249, v251
	v_lshl_add_u64 v[252:253], v[96:97], 0, v[252:253]
	global_store_dwordx4 v[252:253], v[248:251], off
	global_store_dwordx4 v[62:63], v[20:23], off offset:512
	v_add_f32_e32 v17, v18, v19
	v_add_f32_e32 v18, v98, v99
	v_pk_mul_f32 v[70:71], v[80:81], v[20:21]
	v_add_f32_e32 v20, v17, v18
	ds_bpermute_b32 v21, v203, v20
	v_pk_mul_f32 v[68:69], v[82:83], v[22:23]
	v_cvt_pk_bf16_f32 v248, v70, v71
	v_pk_mul_f32 v[18:19], v[66:67], v[56:57]
	v_cvt_pk_bf16_f32 v249, v68, v69
	global_store_dwordx4 v[62:63], v[54:57], off offset:576
	s_waitcnt lgkmcnt(0)
	v_add_f32_e32 v16, v20, v21
	ds_bpermute_b32 v17, v150, v16
	v_pk_mul_f32 v[20:21], v[64:65], v[54:55]
	s_nop 0
	v_cvt_pk_bf16_f32 v250, v20, v21
	v_cvt_pk_bf16_f32 v251, v18, v19
	v_mbcnt_lo_u32_b32 v252, -1, 0
	v_mbcnt_hi_u32_b32 v252, -1, v252
	v_bfe_u32 v252, v252, 4, 1
	v_mul_u32_u24_e32 v252, 24, v252
	v_mov_b32_e32 v253, 0
	v_permlane16_swap_b32 v248, v250
	v_permlane16_swap_b32 v249, v251
	v_lshl_add_u64 v[252:253], v[96:97], 0, v[252:253]
	global_store_dwordx4 v[252:253], v[248:251], off offset:256
	s_and_saveexec_b64 s[4:5], vcc
	s_cbranch_execz .LBB0_1321
	s_waitcnt lgkmcnt(0)
	v_add_f32_e32 v16, v16, v17
	v_mul_f32_e32 v16, 0x4b800000, v16
	v_trunc_f32_e32 v16, v16
	v_mul_f32_e32 v17, 0x2f800000, v16
	v_floor_f32_e32 v17, v17
	v_fmac_f32_e32 v16, 0xcf800000, v17
	v_cvt_u32_f32_e32 v16, v16
	v_cvt_u32_f32_e32 v17, v17
	v_mov_b32_e32 v242, v16
	v_mov_b32_e32 v243, v17
; __device__ __forceinline__ unsigned cvt_pk_bf16(float lo, float hi) { unsigned r; asm volatile("v_cvt_pk_bf16_f32 %0, %1, %2" : "=v"(r) : "v"(lo), "v"(hi)); return r; }
;     __device__ __forceinline__ void operator()(const f32x4 (&acc)[2][2][4][2], const Unit& u, int wr, int wc, int fr_, int fq_) const {
;     ...
;             for (int m = 0; m < 2; ++m) { const int row = row0 + ai * HALF + (2 * mh + m) * 16; const size_t off = (size_t)row * ldc + col0; float ss = 0.f;
; #pragma unroll
;                 for (int bj = 0; bj < 2; ++bj)
; #pragma unroll
;                     for (int n = 0; n < 2; ++n) { const f32x4 o = bs[m][bj][n] + gv[bj][n] * acc[ai][bj][2 * mh + m][n]; *(f32x4*)(out + off + bj * HALF + n * 16) = o;
;                         if constexpr (EMIT) { ss += (o[0] * o[0] + o[1] * o[1]) + (o[2] * o[2] + o[3] * o[3]); const f32x4 y = o * gm[bj][n];
;                             typedef unsigned u32x2_t __attribute__((ext_vector_type(2))); u32x2_t w; w.x = cvt_pk_bf16(y[0], y[1]); w.y = cvt_pk_bf16(y[2], y[3]); *(u32x2_t*)(A2 + off + bj * HALF + n * 16) = w; } }
;                 if constexpr (EMIT) { ss += __shfl_xor(ss, 16); ss += __shfl_xor(ss, 32); if (fq == 0) atomicAdd(ssq + row, (unsigned long long)(ss * 16777216.0f)); } }
.LBB0_1321:
	s_or_b64 exec, exec, s[4:5]
	v_pk_fma_f32 v[14:15], v[14:15], v[106:107], v[46:47]
	v_pk_fma_f32 v[12:13], v[12:13], v[104:105], v[44:45]
	s_waitcnt lgkmcnt(0)
	v_lshlrev_b64 v[16:17], 11, v[48:49]
	v_mul_f32_e32 v18, v13, v13
	v_mul_f32_e32 v19, v15, v15
	v_lshl_add_u64 v[16:17], v[16:17], 0, v[188:189]
	global_store_dwordx4 v[50:51], v[12:15], off
	v_fmac_f32_e32 v18, v12, v12
	v_fmac_f32_e32 v19, v14, v14
	v_pk_mul_f32 v[14:15], v[102:103], v[14:15]
	v_pk_mul_f32 v[12:13], v[100:101], v[12:13]
	v_pk_fma_f32 v[8:9], v[8:9], v[92:93], v[40:41]
	v_cvt_pk_bf16_f32 v248, v12, v13
	v_cvt_pk_bf16_f32 v249, v14, v15
	v_lshl_add_u64 v[14:15], v[16:17], 1, s[14:15]
	v_pk_fma_f32 v[10:11], v[10:11], v[94:95], v[42:43]
	v_mul_f32_e32 v12, v9, v9
	global_store_dwordx4 v[50:51], v[8:11], off offset:64
	v_fmac_f32_e32 v12, v8, v8
	v_mul_f32_e32 v13, v11, v11
	v_pk_mul_f32 v[8:9], v[88:89], v[8:9]
	v_fmac_f32_e32 v13, v10, v10
	v_pk_mul_f32 v[10:11], v[90:91], v[10:11]
	v_cvt_pk_bf16_f32 v250, v8, v9
	v_pk_fma_f32 v[6:7], v[6:7], v[86:87], v[38:39]
	v_cvt_pk_bf16_f32 v251, v10, v11
	v_pk_fma_f32 v[4:5], v[4:5], v[84:85], v[36:37]
	v_mbcnt_lo_u32_b32 v252, -1, 0
	v_mbcnt_hi_u32_b32 v252, -1, v252
	v_bfe_u32 v252, v252, 4, 1
	v_mul_u32_u24_e32 v252, 24, v252
	v_mov_b32_e32 v253, 0
	v_permlane16_swap_b32 v248, v250
	v_permlane16_swap_b32 v249, v251
	v_lshl_add_u64 v[252:253], v[14:15], 0, v[252:253]
	global_store_dwordx4 v[252:253], v[248:251], off
	v_mul_f32_e32 v8, v5, v5
	v_mul_f32_e32 v9, v7, v7
	v_add_f32_e32 v18, v18, v19
	v_add_f32_e32 v12, v12, v13
	v_fmac_f32_e32 v8, v4, v4
	v_fmac_f32_e32 v9, v6, v6
	v_add_f32_e32 v12, v18, v12
	global_store_dwordx4 v[50:51], v[4:7], off offset:512
	v_add_f32_e32 v8, v8, v9
	v_add_f32_e32 v9, v12, v8
	v_pk_mul_f32 v[4:5], v[80:81], v[4:5]
	v_pk_mul_f32 v[6:7], v[82:83], v[6:7]
	v_cvt_pk_bf16_f32 v248, v4, v5
	v_pk_fma_f32 v[4:5], v[2:3], v[74:75], v[34:35]
	v_pk_fma_f32 v[2:3], v[0:1], v[72:73], v[32:33]
	v_mul_f32_e32 v1, v5, v5
	v_mul_f32_e32 v0, v3, v3
	v_fmac_f32_e32 v0, v2, v2
	v_fmac_f32_e32 v1, v4, v4
	v_add_f32_e32 v0, v0, v1
	v_add_f32_e32 v0, v9, v0
	ds_bpermute_b32 v1, v203, v0
	v_cvt_pk_bf16_f32 v249, v6, v7
	global_store_dwordx4 v[50:51], v[2:5], off offset:576
	s_waitcnt lgkmcnt(0)
	v_add_f32_e32 v0, v0, v1
	ds_bpermute_b32 v1, v150, v0
	v_pk_mul_f32 v[2:3], v[64:65], v[2:3]
	v_pk_mul_f32 v[4:5], v[66:67], v[4:5]
	v_cvt_pk_bf16_f32 v250, v2, v3
	s_nop 0
	v_cvt_pk_bf16_f32 v251, v4, v5
	v_mbcnt_lo_u32_b32 v252, -1, 0
	v_mbcnt_hi_u32_b32 v252, -1, v252
	v_bfe_u32 v252, v252, 4, 1
	v_mul_u32_u24_e32 v252, 24, v252
	v_mov_b32_e32 v253, 0
	v_permlane16_swap_b32 v248, v250
	v_permlane16_swap_b32 v249, v251
	v_lshl_add_u64 v[252:253], v[14:15], 0, v[252:253]
	global_store_dwordx4 v[252:253], v[248:251], off offset:256
	s_and_saveexec_b64 s[4:5], vcc
	s_cbranch_execz .LBB0_1323
	s_waitcnt lgkmcnt(0)
	v_add_f32_e32 v0, v0, v1
	v_mul_f32_e32 v0, 0x4b800000, v0
	v_trunc_f32_e32 v0, v0
	v_mul_f32_e32 v1, 0x2f800000, v0
	v_floor_f32_e32 v1, v1
	v_fmac_f32_e32 v0, 0xcf800000, v1
	v_cvt_u32_f32_e32 v0, v0
	v_cvt_u32_f32_e32 v1, v1
	v_mov_b32_e32 v244, v0
	v_mov_b32_e32 v245, v1
	global_atomic_add_x2 v[246:247], v[230:231], off
	global_atomic_add_x2 v[246:247], v[232:233], off offset:128
	global_atomic_add_x2 v[246:247], v[234:235], off offset:256
	global_atomic_add_x2 v[246:247], v[236:237], off offset:384
	global_atomic_add_x2 v[246:247], v[238:239], off offset:1024
	global_atomic_add_x2 v[246:247], v[240:241], off offset:1152
	global_atomic_add_x2 v[246:247], v[242:243], off offset:1280
	global_atomic_add_x2 v[246:247], v[244:245], off offset:1408
